# P3 prompt attention loops: redundant fmaxf operand canonicalisations (v_max x,x) and '0 + x' in the row-sum chain replaced by s_nop 0 (identities for finite scores; loops are VALU-issue bound)
# speedup vs baseline: 1.0043x; 1.0006x over previous
.LBB0_1903:
	v_lshlrev_b32_e32 v2, 1, v38
	v_and_b32_e32 v2, 32, v2
	v_add3_u32 v2, 16, v2, v39
	v_lshlrev_b32_e32 v38, 8, v194
	v_and_b32_e32 v39, 0xc0, v40
	v_add3_u32 v206, v2, v38, v39
	s_nop 2
	s_nop 0
	s_nop 0
	v_max_f32_e32 v2, v4, v5
	v_max3_f32 v38, v6, v7, v21
	v_max3_f32 v2, v2, v20, v22
	v_max3_f32 v2, v2, v23, v8
	v_max3_f32 v38, v38, v10, v11
	v_max3_f32 v2, v2, v9, v24
	v_max3_f32 v38, v38, v26, v27
	v_max3_f32 v2, v2, v25, v12
	v_max3_f32 v38, v38, v14, v15
	v_max3_f32 v2, v2, v13, v28
	v_max3_f32 v38, v38, v30, v31
	v_max3_f32 v2, v2, v29, v16
	v_max3_f32 v38, v38, v18, v19
	v_max3_f32 v2, v2, v17, v32
	v_max3_f32 v38, v38, v34, v35
	v_max3_f32 v2, v2, v33, v38
	v_mov_b32_e32 v38, v2
	s_nop 1
	v_permlane32_swap_b32_e32 v2, v38
	v_max_f32_e32 v38, v38, v38
	v_max_f32_e32 v2, v2, v2
	v_max_f32_e32 v208, v2, v38
	v_sub_f32_e32 v2, v4, v208
	v_exp_f32_e32 v98, v2
	v_sub_f32_e32 v2, v20, v208
	v_exp_f32_e32 v82, v2
	v_sub_f32_e32 v2, v5, v208
	v_exp_f32_e32 v99, v2
	v_sub_f32_e32 v2, v21, v208
	v_exp_f32_e32 v83, v2
	v_sub_f32_e32 v2, v6, v208
	v_exp_f32_e32 v100, v2
	v_sub_f32_e32 v2, v22, v208
	v_exp_f32_e32 v84, v2
	v_sub_f32_e32 v2, v7, v208
	v_exp_f32_e32 v101, v2
	v_sub_f32_e32 v2, v23, v208
	v_exp_f32_e32 v85, v2
	v_sub_f32_e32 v2, v8, v208
	v_exp_f32_e32 v102, v2
	v_sub_f32_e32 v2, v24, v208
	v_exp_f32_e32 v86, v2
	v_sub_f32_e32 v2, v9, v208
	v_exp_f32_e32 v103, v2
	v_sub_f32_e32 v2, v25, v208
	v_exp_f32_e32 v87, v2
	v_sub_f32_e32 v2, v10, v208
	v_exp_f32_e32 v104, v2
	v_sub_f32_e32 v2, v26, v208
	v_exp_f32_e32 v88, v2
	v_sub_f32_e32 v2, v11, v208
	v_exp_f32_e32 v105, v2
	v_sub_f32_e32 v2, v27, v208
	v_exp_f32_e32 v89, v2
	v_sub_f32_e32 v2, v12, v208
	v_exp_f32_e32 v106, v2
	v_sub_f32_e32 v2, v28, v208
	v_exp_f32_e32 v90, v2
	v_sub_f32_e32 v2, v13, v208
	v_exp_f32_e32 v107, v2
	v_sub_f32_e32 v2, v29, v208
	v_exp_f32_e32 v91, v2
	v_sub_f32_e32 v2, v14, v208
	v_exp_f32_e32 v108, v2
	v_sub_f32_e32 v2, v30, v208
	v_exp_f32_e32 v92, v2
	v_sub_f32_e32 v2, v15, v208
	v_exp_f32_e32 v109, v2
	v_sub_f32_e32 v2, v31, v208
	v_exp_f32_e32 v93, v2
	v_sub_f32_e32 v2, v16, v208
	s_add_i32 s1, s71, 0x100
	v_exp_f32_e32 v110, v2
	v_sub_f32_e32 v2, v32, v208
	s_ashr_i32 s79, s1, 6
	s_and_b32 s1, s4, 0x3fffffc0
	v_exp_f32_e32 v94, v2
	v_sub_f32_e32 v2, v17, v208
	s_lshl_b32 s1, s1, 2
	v_exp_f32_e32 v111, v2
	v_sub_f32_e32 v2, v33, v208
	s_add_i32 s23, s1, 16
	v_exp_f32_e32 v95, v2
	v_sub_f32_e32 v2, v18, v208
	s_waitcnt vmcnt(0) lgkmcnt(0)
	s_barrier
	v_exp_f32_e32 v112, v2
	v_sub_f32_e32 v2, v34, v208
	v_lshl_add_u64 v[4:5], v[186:187], 0, s[14:15]
	s_mov_b32 s1, m0
	s_mov_b32 m0, s77
	s_nop 0
	global_load_lds_dwordx4 v[4:5], off
	s_mov_b32 m0, s1
	s_cmp_lg_u32 16, -1
	v_exp_f32_e32 v96, v2
	v_sub_f32_e32 v2, v19, v208
	s_cselect_b32 s1, 16, 0
	v_exp_f32_e32 v113, v2
	v_sub_f32_e32 v2, v35, v208
	s_add_i32 s0, s1, s0
	v_exp_f32_e32 v97, v2
	v_lshl_add_u64 v[188:189], v[36:37], 0, s[10:11]
	s_add_i32 s0, s0, 0x8000
	s_mov_b32 s1, m0
	s_mov_b32 m0, s0
	s_nop 0
	global_load_lds_dwordx4 v[188:189], off
	s_mov_b32 m0, s1
	v_lshl_add_u32 v2, v194, 4, 16
	ds_read_b128 v[174:177], v210 offset:8192
	ds_read_b128 v[170:173], v210 offset:10240
	ds_read_b128 v[166:169], v224 offset:8192
	ds_read_b128 v[162:165], v224 offset:10240
	ds_read_b128 v[158:161], v210 offset:12288
	ds_read_b128 v[154:157], v210 offset:14336
	ds_read_b128 v[150:153], v224 offset:12288
	ds_read_b128 v[146:149], v224 offset:14336
	s_waitcnt vmcnt(2) lgkmcnt(0)
	s_barrier
	v_add_u32_e32 v2, 0x14900, v2
	ds_read_b128 v[66:69], v2
	ds_read_b128 v[70:73], v2 offset:32
	ds_read_b128 v[50:53], v2 offset:128
	ds_read_b128 v[54:57], v2 offset:160
	ds_read_b128 v[74:77], v2 offset:64
	ds_read_b128 v[78:81], v2 offset:96
	ds_read_b128 v[58:61], v2 offset:192
	ds_read_b128 v[62:65], v2 offset:224
	s_mov_b32 s8, 1
	s_mov_b32 s35, 0
	s_cmp_lt_i32 s79, 7
	v_cmp_gt_u32_e64 s[0:1], 32, v202
	v_lshl_add_u32 v207, v204, 2, s23
	s_cbranch_scc1 .LBB0_1919
	v_mov_b32_e32 v16, v3
	v_mov_b32_e32 v17, v3
	v_lshl_add_u64 v[190:191], v[36:37], 0, s[14:15]
	v_mov_b32_e32 v2, v3
	v_mov_b32_e32 v4, v3
	v_mov_b32_e32 v5, v3
	v_mov_b32_e32 v6, v3
	v_mov_b32_e32 v7, v3
	v_mov_b32_e32 v8, v3
	v_mov_b32_e32 v9, v3
	v_mov_b32_e32 v10, v3
	v_mov_b32_e32 v11, v3
	v_mov_b32_e32 v12, v3
	v_mov_b32_e32 v13, v3
	v_mov_b32_e32 v14, v3
	v_mov_b32_e32 v15, v3
	v_mov_b64_e32 v[48:49], v[16:17]
	v_mov_b64_e32 v[32:33], v[16:17]
	s_add_i32 s36, s79, -5
	v_add_u32_e32 v196, s65, v195
	v_lshl_add_u64 v[192:193], v[186:187], 0, s[16:17]
	s_mov_b32 s4, 0
	s_movk_i32 s35, 0x4000
	s_movk_i32 s37, 0x2000
	v_mov_b32_e32 v211, 0
	v_mov_b64_e32 v[46:47], v[14:15]
	v_mov_b64_e32 v[44:45], v[12:13]
	v_mov_b64_e32 v[42:43], v[10:11]
	v_mov_b64_e32 v[40:41], v[8:9]
	v_mov_b64_e32 v[38:39], v[6:7]
	v_mov_b64_e32 v[36:37], v[4:5]
	v_mov_b64_e32 v[34:35], v[2:3]
	v_mov_b64_e32 v[30:31], v[14:15]
	v_mov_b64_e32 v[28:29], v[12:13]
	v_mov_b64_e32 v[26:27], v[10:11]
	v_mov_b64_e32 v[24:25], v[8:9]
	v_mov_b64_e32 v[22:23], v[6:7]
	v_mov_b64_e32 v[20:21], v[4:5]
	v_mov_b64_e32 v[18:19], v[2:3]
.LBB0_1905:
	v_add_u32_e32 v2, s4, v206
	ds_read_b64_tr_b16 v[182:183], v2 offset:24576
	ds_read_b64_tr_b16 v[184:185], v2 offset:25088
	s_waitcnt lgkmcnt(4)
	v_mfma_f32_32x32x16_bf16 v[66:81], v[174:177], v[126:129], v[66:81]
	v_add_f32_e32 v4, v98, v99
	v_add_f32_e32 v4, v100, v4
	v_add_f32_e32 v4, v101, v4
	v_add_f32_e32 v4, v102, v4
	v_add_f32_e32 v4, v103, v4
	v_cvt_pk_bf16_f32 v142, v98, v99
	v_cvt_pk_bf16_f32 v143, v100, v101
	ds_read_b64_tr_b16 v[178:179], v2 offset:28672
	ds_read_b64_tr_b16 v[180:181], v2 offset:29184
	s_waitcnt lgkmcnt(4)
	v_mfma_f32_32x32x16_bf16 v[50:65], v[170:173], v[126:129], v[50:65]
	v_add_f32_e32 v4, v104, v4
	v_add_f32_e32 v4, v105, v4
	v_add_f32_e32 v4, v106, v4
	v_add_f32_e32 v4, v107, v4
	v_cvt_pk_bf16_f32 v144, v102, v103
	v_cvt_pk_bf16_f32 v145, v104, v105
	ds_read_b64_tr_b16 v[12:13], v2 offset:25600
	ds_read_b64_tr_b16 v[14:15], v2 offset:26112
	v_mfma_f32_32x32x16_bf16 v[66:81], v[166:169], v[122:125], v[66:81]
	v_add_f32_e32 v4, v108, v4
	v_add_f32_e32 v4, v109, v4
	v_add_f32_e32 v4, v110, v4
	v_add_f32_e32 v4, v111, v4
	v_cvt_pk_bf16_f32 v138, v106, v107
	v_cvt_pk_bf16_f32 v139, v108, v109
	ds_read_b64_tr_b16 v[8:9], v2 offset:29696
	ds_read_b64_tr_b16 v[10:11], v2 offset:30208
	v_mfma_f32_32x32x16_bf16 v[50:65], v[162:165], v[122:125], v[50:65]
	v_add_f32_e32 v4, v112, v4
	v_add_f32_e32 v4, v113, v4
	v_add_f32_e32 v4, v82, v4
	v_add_f32_e32 v16, v83, v4
	v_cvt_pk_bf16_f32 v140, v110, v111
	v_cvt_pk_bf16_f32 v141, v112, v113
	ds_read_b64_tr_b16 v[4:5], v2 offset:26624
	ds_read_b64_tr_b16 v[6:7], v2 offset:27136
	v_mfma_f32_32x32x16_bf16 v[66:81], v[158:161], v[118:121], v[66:81]
	v_add_f32_e32 v16, v84, v16
	v_add_f32_e32 v16, v85, v16
	v_add_f32_e32 v16, v86, v16
	v_add_f32_e32 v16, v87, v16
	v_cvt_pk_bf16_f32 v134, v82, v83
	v_cvt_pk_bf16_f32 v135, v84, v85
	ds_read_b64_tr_b16 v[174:175], v2 offset:30720
	ds_read_b64_tr_b16 v[176:177], v2 offset:31232
	v_mfma_f32_32x32x16_bf16 v[50:65], v[154:157], v[118:121], v[50:65]
	v_add_f32_e32 v16, v88, v16
	v_add_f32_e32 v16, v89, v16
	v_add_f32_e32 v16, v90, v16
	v_add_f32_e32 v16, v91, v16
	v_cvt_pk_bf16_f32 v136, v86, v87
	v_cvt_pk_bf16_f32 v137, v88, v89
	ds_read_b64_tr_b16 v[170:171], v2 offset:27648
	ds_read_b64_tr_b16 v[172:173], v2 offset:28160
	v_mfma_f32_32x32x16_bf16 v[66:81], v[150:153], v[114:117], v[66:81]
	v_add_f32_e32 v16, v92, v16
	v_add_f32_e32 v16, v93, v16
	v_add_f32_e32 v16, v94, v16
	v_add_f32_e32 v16, v95, v16
	v_cvt_pk_bf16_f32 v130, v90, v91
	v_cvt_pk_bf16_f32 v131, v92, v93
	ds_read_b64_tr_b16 v[166:167], v2 offset:31744
	ds_read_b64_tr_b16 v[168:169], v2 offset:32256
	v_mfma_f32_32x32x16_bf16 v[50:65], v[146:149], v[114:117], v[50:65]
	v_add_f32_e32 v2, v96, v16
	v_add_f32_e32 v2, v97, v2
	s_nop 0
	v_cvt_pk_bf16_f32 v132, v94, v95
	v_cvt_pk_bf16_f32 v133, v96, v97
	s_nop 0
	v_add_f32_e32 v16, v211, v2
	s_nop 0
	s_nop 0
	v_max_f32_e32 v2, v66, v67
	s_nop 2
	v_max3_f32 v17, v68, v69, v51
	v_max3_f32 v2, v2, v50, v52
	v_max3_f32 v2, v2, v53, v70
	v_max3_f32 v17, v17, v72, v73
	v_max3_f32 v2, v2, v71, v54
	v_max3_f32 v17, v17, v56, v57
	v_max3_f32 v2, v2, v55, v74
	v_max3_f32 v17, v17, v76, v77
	v_max3_f32 v2, v2, v75, v58
	v_max3_f32 v17, v17, v60, v61
	v_max3_f32 v2, v2, v59, v78
	v_max3_f32 v17, v17, v80, v81
	v_max3_f32 v2, v2, v79, v62
	v_max3_f32 v17, v17, v64, v65
	v_max3_f32 v2, v2, v63, v17
	v_mov_b32_e32 v17, v2
	s_nop 1
	v_permlane32_swap_b32_e32 v2, v17
	s_nop 0
	s_nop 0
	v_max_f32_e32 v2, v2, v17
	v_lshl_add_u64 v[82:83], v[192:193], 0, s[18:19]
	s_add_i32 s4, s37, s77
	s_mov_b32 s5, m0
	s_mov_b32 m0, s4
	s_nop 0
	global_load_lds_dwordx4 v[82:83], off
	s_mov_b32 m0, s5
	v_sub_f32_e32 v2, v2, v208
	v_lshl_add_u64 v[82:83], v[190:191], 0, s[18:19]
	s_add_i32 s4, s35, s78
	s_mov_b32 s5, m0
	s_mov_b32 m0, s4
	s_nop 0
	global_load_lds_dwordx4 v[82:83], off
	s_mov_b32 m0, s5
	v_cmp_lt_f32_e32 vcc, s66, v2
	s_cmp_lg_u64 vcc, 0
	s_cselect_b64 s[6:7], -1, 0
	s_cbranch_vccz .LBB0_1909
	v_max_f32_e32 v2, v2, v2
	v_max_f32_e32 v17, 0, v2
	v_exp_f32_e64 v2, -v17
	s_and_saveexec_b64 s[4:5], s[0:1]
	ds_write_b32 v207, v2 offset:49152
	s_or_b64 exec, exec, s[4:5]
	v_add_f32_e32 v208, v208, v17
	v_mul_f32_e32 v16, v16, v2

.LBB0_1911:
	s_add_i32 s4, s35, 0x2000
	s_cmpk_lg_i32 s35, 0x4000
	s_cselect_b32 s80, s4, 0
	v_add_u32_e32 v17, s37, v206
	ds_read_b64_tr_b16 v[170:171], v17 offset:24576
	ds_read_b64_tr_b16 v[172:173], v17 offset:25088
	s_waitcnt lgkmcnt(9)
	v_mfma_f32_32x32x16_bf16 v[98:113], v[162:165], v[126:129], v[98:113]
	v_add_f32_e32 v130, v66, v67
	v_add_f32_e32 v130, v68, v130
	v_add_f32_e32 v130, v69, v130
	v_add_f32_e32 v130, v70, v130
	v_add_f32_e32 v130, v71, v130
	v_cvt_pk_bf16_f32 v142, v66, v67
	v_cvt_pk_bf16_f32 v143, v68, v69
	ds_read_b64_tr_b16 v[166:167], v17 offset:28672
	ds_read_b64_tr_b16 v[168:169], v17 offset:29184
	s_waitcnt lgkmcnt(10)
	v_mfma_f32_32x32x16_bf16 v[82:97], v[154:157], v[126:129], v[82:97]
	v_add_f32_e32 v66, v72, v130
	v_add_f32_e32 v66, v73, v66
	v_add_f32_e32 v66, v74, v66
	v_add_f32_e32 v66, v75, v66
	v_cvt_pk_bf16_f32 v144, v70, v71
	v_cvt_pk_bf16_f32 v145, v72, v73
	ds_read_b64_tr_b16 v[162:163], v17 offset:25600
	ds_read_b64_tr_b16 v[164:165], v17 offset:26112
	s_waitcnt lgkmcnt(11)
	v_mfma_f32_32x32x16_bf16 v[98:113], v[158:161], v[122:125], v[98:113]
	v_add_f32_e32 v66, v76, v66
	v_add_f32_e32 v66, v77, v66
	v_add_f32_e32 v66, v78, v66
	v_add_f32_e32 v66, v79, v66
	v_cvt_pk_bf16_f32 v138, v74, v75
	v_cvt_pk_bf16_f32 v139, v76, v77
	ds_read_b64_tr_b16 v[154:155], v17 offset:29696
	ds_read_b64_tr_b16 v[156:157], v17 offset:30208
	s_waitcnt lgkmcnt(12)
	v_mfma_f32_32x32x16_bf16 v[82:97], v[146:149], v[122:125], v[82:97]
	v_add_f32_e32 v66, v80, v66
	v_add_f32_e32 v66, v81, v66
	v_add_f32_e32 v66, v50, v66
	v_add_f32_e32 v66, v51, v66
	v_cvt_pk_bf16_f32 v140, v78, v79
	v_cvt_pk_bf16_f32 v141, v80, v81
	ds_read_b64_tr_b16 v[146:147], v17 offset:26624
	ds_read_b64_tr_b16 v[148:149], v17 offset:27136
	s_waitcnt lgkmcnt(13)
	v_mfma_f32_32x32x16_bf16 v[98:113], v[150:153], v[118:121], v[98:113]
	v_add_f32_e32 v66, v52, v66
	v_add_f32_e32 v66, v53, v66
	v_add_f32_e32 v66, v54, v66
	v_add_f32_e32 v66, v55, v66
	v_cvt_pk_bf16_f32 v134, v50, v51
	v_cvt_pk_bf16_f32 v135, v52, v53
	ds_read_b64_tr_b16 v[182:183], v17 offset:30720
	ds_read_b64_tr_b16 v[184:185], v17 offset:31232
	s_waitcnt lgkmcnt(14)
	v_mfma_f32_32x32x16_bf16 v[82:97], v[8:11], v[118:121], v[82:97]
	v_add_f32_e32 v50, v56, v66
	v_add_f32_e32 v50, v57, v50
	v_add_f32_e32 v50, v58, v50
	v_add_f32_e32 v50, v59, v50
	v_cvt_pk_bf16_f32 v136, v54, v55
	v_cvt_pk_bf16_f32 v137, v56, v57
	ds_read_b64_tr_b16 v[178:179], v17 offset:27648
	ds_read_b64_tr_b16 v[180:181], v17 offset:28160
	s_waitcnt lgkmcnt(14)
	v_mfma_f32_32x32x16_bf16 v[98:113], v[12:15], v[114:117], v[98:113]
	v_add_f32_e32 v8, v60, v50
	v_add_f32_e32 v8, v61, v8
	v_add_f32_e32 v8, v62, v8
	v_add_f32_e32 v50, v63, v8
	v_cvt_pk_bf16_f32 v130, v58, v59
	v_cvt_pk_bf16_f32 v131, v60, v61
	ds_read_b64_tr_b16 v[8:9], v17 offset:31744
	ds_read_b64_tr_b16 v[10:11], v17 offset:32256
	v_mfma_f32_32x32x16_bf16 v[82:97], v[4:7], v[114:117], v[82:97]
	v_add_f32_e32 v12, v64, v50
	v_add_f32_e32 v12, v65, v12
	s_nop 0
	v_cvt_pk_bf16_f32 v132, v62, v63
	v_cvt_pk_bf16_f32 v133, v64, v65
	s_nop 0
	s_nop 0
	v_max_f32_e32 v4, v98, v99
	s_nop 4
	v_max3_f32 v5, v100, v101, v83
	v_max3_f32 v4, v4, v82, v84
	v_max3_f32 v4, v4, v85, v102
	v_max3_f32 v5, v5, v104, v105
	v_max3_f32 v4, v4, v103, v86
	v_max3_f32 v5, v5, v88, v89
	v_max3_f32 v4, v4, v87, v106
	v_max3_f32 v5, v5, v108, v109
	v_max3_f32 v4, v4, v107, v90
	v_max3_f32 v5, v5, v92, v93
	v_max3_f32 v4, v4, v91, v110
	v_max3_f32 v5, v5, v112, v113
	v_max3_f32 v4, v4, v111, v94
	v_max3_f32 v5, v5, v96, v97
	v_max3_f32 v4, v4, v95, v5
	v_mov_b32_e32 v5, v4
	s_nop 1
	v_permlane32_swap_b32_e32 v4, v5
	s_nop 0
	s_nop 0
	v_max_f32_e32 v4, v4, v5
	s_add_i32 s4, s35, s77
	s_mov_b32 s5, m0
	s_mov_b32 m0, s4
	s_nop 0
	global_load_lds_dwordx4 v[192:193], off
	s_mov_b32 m0, s5
	v_sub_f32_e32 v4, v4, v208
	s_add_i32 s4, s80, s78
	s_mov_b32 s5, m0
	s_mov_b32 m0, s4
	s_nop 0
	global_load_lds_dwordx4 v[190:191], off
	s_mov_b32 m0, s5
	v_cmp_lt_f32_e32 vcc, s66, v4
	s_cmp_lg_u64 vcc, 0
	v_add_f32_e32 v211, v16, v12
	s_cselect_b64 s[6:7], -1, 0
	s_cbranch_vccz .LBB0_1915
	v_max_f32_e32 v4, v4, v4
	v_max_f32_e32 v5, 0, v4
	v_exp_f32_e64 v4, -v5
	s_and_saveexec_b64 s[4:5], s[0:1]
	ds_write_b32 v207, v4 offset:49152
	s_or_b64 exec, exec, s[4:5]
	v_add_f32_e32 v208, v208, v5
	v_mul_f32_e32 v211, v211, v4

.LBB0_1924:
	v_add_u32_e32 v6, s35, v206
	ds_read_b64_tr_b16 v[190:191], v6 offset:24576
	ds_read_b64_tr_b16 v[192:193], v6 offset:25088
	s_waitcnt lgkmcnt(4)
	v_mfma_f32_32x32x16_bf16 v[66:81], v[174:177], v[126:129], v[66:81]
	v_add_f32_e32 v4, v98, v99
	v_add_f32_e32 v4, v100, v4
	v_add_f32_e32 v4, v101, v4
	v_add_f32_e32 v4, v102, v4
	v_add_f32_e32 v4, v103, v4
	v_cvt_pk_bf16_f32 v142, v98, v99
	v_cvt_pk_bf16_f32 v143, v100, v101
	ds_read_b64_tr_b16 v[174:175], v6 offset:28672
	ds_read_b64_tr_b16 v[176:177], v6 offset:29184
	s_waitcnt lgkmcnt(4)
	v_mfma_f32_32x32x16_bf16 v[50:65], v[170:173], v[126:129], v[50:65]
	v_add_f32_e32 v4, v104, v4
	v_add_f32_e32 v4, v105, v4
	v_add_f32_e32 v4, v106, v4
	v_add_f32_e32 v4, v107, v4
	v_cvt_pk_bf16_f32 v144, v102, v103
	v_cvt_pk_bf16_f32 v145, v104, v105
	ds_read_b64_tr_b16 v[186:187], v6 offset:25600
	ds_read_b64_tr_b16 v[188:189], v6 offset:26112
	v_mfma_f32_32x32x16_bf16 v[66:81], v[166:169], v[122:125], v[66:81]
	v_add_f32_e32 v4, v108, v4
	v_add_f32_e32 v4, v109, v4
	v_add_f32_e32 v4, v110, v4
	v_add_f32_e32 v4, v111, v4
	v_cvt_pk_bf16_f32 v138, v106, v107
	v_cvt_pk_bf16_f32 v139, v108, v109
	ds_read_b64_tr_b16 v[182:183], v6 offset:29696
	ds_read_b64_tr_b16 v[184:185], v6 offset:30208
	v_mfma_f32_32x32x16_bf16 v[50:65], v[162:165], v[122:125], v[50:65]
	v_add_f32_e32 v4, v112, v4
	v_add_f32_e32 v4, v113, v4
	v_add_f32_e32 v4, v82, v4
	v_add_f32_e32 v4, v83, v4
	v_cvt_pk_bf16_f32 v140, v110, v111
	v_cvt_pk_bf16_f32 v141, v112, v113
	ds_read_b64_tr_b16 v[178:179], v6 offset:26624
	ds_read_b64_tr_b16 v[180:181], v6 offset:27136
	v_mfma_f32_32x32x16_bf16 v[66:81], v[158:161], v[118:121], v[66:81]
	v_add_f32_e32 v4, v84, v4
	v_add_f32_e32 v4, v85, v4
	v_add_f32_e32 v4, v86, v4
	v_add_f32_e32 v4, v87, v4
	v_cvt_pk_bf16_f32 v134, v82, v83
	v_cvt_pk_bf16_f32 v135, v84, v85
	ds_read_b64_tr_b16 v[12:13], v6 offset:30720
	ds_read_b64_tr_b16 v[14:15], v6 offset:31232
	v_mfma_f32_32x32x16_bf16 v[50:65], v[154:157], v[118:121], v[50:65]
	v_add_f32_e32 v4, v88, v4
	v_add_f32_e32 v4, v89, v4
	v_add_f32_e32 v4, v90, v4
	v_add_f32_e32 v4, v91, v4
	v_cvt_pk_bf16_f32 v136, v86, v87
	v_cvt_pk_bf16_f32 v137, v88, v89
	ds_read_b64_tr_b16 v[8:9], v6 offset:27648
	ds_read_b64_tr_b16 v[10:11], v6 offset:28160
	v_mfma_f32_32x32x16_bf16 v[66:81], v[150:153], v[114:117], v[66:81]
	v_add_f32_e32 v4, v92, v4
	v_add_f32_e32 v4, v93, v4
	v_add_f32_e32 v4, v94, v4
	v_add_f32_e32 v82, v95, v4
	v_cvt_pk_bf16_f32 v130, v90, v91
	v_cvt_pk_bf16_f32 v131, v92, v93
	ds_read_b64_tr_b16 v[4:5], v6 offset:31744
	ds_read_b64_tr_b16 v[6:7], v6 offset:32256
	v_mfma_f32_32x32x16_bf16 v[50:65], v[146:149], v[114:117], v[50:65]
	v_add_f32_e32 v82, v96, v82
	v_add_f32_e32 v82, v97, v82
	s_nop 0
	v_cvt_pk_bf16_f32 v132, v94, v95
	v_cvt_pk_bf16_f32 v133, v96, v97
	s_add_i32 s4, s8, 1
	s_cmp_ge_i32 s4, s79
	s_cselect_b64 s[34:35], -1, 0
	s_and_b64 vcc, exec, s[34:35]
	s_cbranch_vccnz .LBB0_1926
	s_add_i32 s4, s80, s77
	v_lshl_add_u64 v[84:85], v[200:201], 0, s[18:19]
	s_mov_b32 s5, m0
	s_mov_b32 m0, s4
	s_nop 0
	global_load_lds_dwordx4 v[84:85], off
	s_mov_b32 m0, s5
.LBB0_1926:
	v_add_u32_e32 v83, 0xffffffa5, v212
	v_add_f32_e32 v211, v211, v82
	v_add_u32_e32 v82, 0xffffff85, v212
	v_cmp_le_i32_e32 vcc, v83, v209
	s_add_i32 s4, s84, s78
	s_mov_b32 s5, m0
	s_mov_b32 m0, s4
	s_nop 0
	global_load_lds_dwordx4 v[16:17], off
	s_mov_b32 m0, s5
	s_nop 0
	v_cndmask_b32_e32 v50, v199, v50, vcc
	v_cmp_lt_i32_e32 vcc, v82, v209
	s_nop 1
	v_cndmask_b32_e32 v67, v199, v67, vcc
	v_cmp_le_i32_e32 vcc, v82, v209
	v_add_u32_e32 v82, 0xffffffa6, v212
	s_nop 0
	v_cndmask_b32_e32 v66, v199, v66, vcc
	v_cmp_le_i32_e32 vcc, v82, v209
	v_add_u32_e32 v82, 0xffffff87, v212
	v_max_f32_e32 v83, v66, v66
	v_cndmask_b32_e32 v51, v199, v51, vcc
	v_cmp_le_i32_e32 vcc, v82, v209
	v_add_u32_e32 v82, 0xffffffa7, v212
	s_nop 0
	v_cndmask_b32_e32 v68, v199, v68, vcc
	v_cmp_le_i32_e32 vcc, v82, v209
	v_add_u32_e32 v82, 0xffffff88, v212
	s_nop 0
	v_cndmask_b32_e32 v52, v199, v52, vcc
	v_cmp_le_i32_e32 vcc, v82, v209
	v_add_u32_e32 v82, 0xffffffa8, v212
	s_nop 0
	v_cndmask_b32_e32 v69, v199, v69, vcc
	v_cmp_le_i32_e32 vcc, v82, v209
	v_add_u32_e32 v82, 0xffffff8d, v212
	s_nop 0
	v_cndmask_b32_e32 v53, v199, v53, vcc
	v_cmp_le_i32_e32 vcc, v82, v209
	v_add_u32_e32 v82, 0xffffffad, v212
	s_nop 0
	v_cndmask_b32_e32 v70, v199, v70, vcc
	v_cmp_le_i32_e32 vcc, v82, v209
	v_add_u32_e32 v82, 0xffffff8e, v212
	s_nop 0
	v_cndmask_b32_e32 v54, v199, v54, vcc
	v_cmp_le_i32_e32 vcc, v82, v209
	v_add_u32_e32 v82, 0xffffffae, v212
	s_nop 0
	v_cndmask_b32_e32 v71, v199, v71, vcc
	v_cmp_le_i32_e32 vcc, v82, v209
	v_add_u32_e32 v82, 0xffffff8f, v212
	s_nop 0
	v_cndmask_b32_e32 v55, v199, v55, vcc
	v_cmp_le_i32_e32 vcc, v82, v209
	v_add_u32_e32 v82, 0xffffffaf, v212
	s_nop 0
	v_cndmask_b32_e32 v72, v199, v72, vcc
	v_cmp_le_i32_e32 vcc, v82, v209
	v_add_u32_e32 v82, 0xffffff90, v212
	s_nop 0
	v_cndmask_b32_e32 v56, v199, v56, vcc
	v_cmp_le_i32_e32 vcc, v82, v209
	v_add_u32_e32 v82, 0xffffffb0, v212
	s_nop 0
	v_cndmask_b32_e32 v73, v199, v73, vcc
	v_cmp_le_i32_e32 vcc, v82, v209
	v_add_u32_e32 v82, 0xffffff95, v212
	s_nop 0
	v_cndmask_b32_e32 v57, v199, v57, vcc
	v_cmp_le_i32_e32 vcc, v82, v209
	v_add_u32_e32 v82, 0xffffffb5, v212
	s_nop 0
	v_cndmask_b32_e32 v74, v199, v74, vcc
	v_cmp_le_i32_e32 vcc, v82, v209
	v_add_u32_e32 v82, 0xffffff96, v212
	s_nop 0
	v_cndmask_b32_e32 v58, v199, v58, vcc
	v_cmp_le_i32_e32 vcc, v82, v209
	v_add_u32_e32 v82, 0xffffffb6, v212
	s_nop 0
	v_cndmask_b32_e32 v75, v199, v75, vcc
	v_cmp_le_i32_e32 vcc, v82, v209
	v_add_u32_e32 v82, 0xffffff97, v212
	s_nop 0
	v_cndmask_b32_e32 v59, v199, v59, vcc
	v_cmp_le_i32_e32 vcc, v82, v209
	v_add_u32_e32 v82, 0xffffffb7, v212
	s_nop 0
	v_cndmask_b32_e32 v76, v199, v76, vcc
	v_cmp_le_i32_e32 vcc, v82, v209
	v_add_u32_e32 v82, 0xffffff98, v212
	s_nop 0
	v_cndmask_b32_e32 v60, v199, v60, vcc
	v_cmp_le_i32_e32 vcc, v82, v209
	v_add_u32_e32 v82, 0xffffffb8, v212
	s_nop 0
	v_cndmask_b32_e32 v77, v199, v77, vcc
	v_cmp_le_i32_e32 vcc, v82, v209
	v_add_u32_e32 v82, 0xffffff9d, v212
	s_nop 0
	v_cndmask_b32_e32 v61, v199, v61, vcc
	v_cmp_le_i32_e32 vcc, v82, v209
	v_add_u32_e32 v82, 0xffffffbd, v212
	s_nop 0
	v_cndmask_b32_e32 v78, v199, v78, vcc
	v_cmp_le_i32_e32 vcc, v82, v209
	v_add_u32_e32 v82, 0xffffff9e, v212
	s_nop 0
	v_cndmask_b32_e32 v62, v199, v62, vcc
	v_cmp_le_i32_e32 vcc, v82, v209
	v_add_u32_e32 v82, 0xffffffbe, v212
	s_nop 0
	v_cndmask_b32_e32 v79, v199, v79, vcc
	v_cmp_le_i32_e32 vcc, v82, v209
	v_add_u32_e32 v82, 0xffffff9f, v212
	s_nop 0
	v_cndmask_b32_e32 v63, v199, v63, vcc
	v_cmp_le_i32_e32 vcc, v82, v209
	v_add_u32_e32 v82, 0xffffffbf, v212
	s_nop 0
	v_cndmask_b32_e32 v80, v199, v80, vcc
	v_cmp_le_i32_e32 vcc, v82, v209
	v_add_u32_e32 v82, 0xffffffa0, v212
	s_nop 0
	v_cndmask_b32_e32 v64, v199, v64, vcc
	v_cmp_le_i32_e32 vcc, v82, v209
	v_subrev_u32_e32 v82, 64, v212
	s_nop 0
	v_cndmask_b32_e32 v81, v199, v81, vcc
	v_cmp_le_i32_e32 vcc, v82, v209
	v_max_f32_e32 v82, v67, v67
	v_max_f32_e32 v82, v83, v82
	v_max3_f32 v83, v68, v69, v51
	v_max3_f32 v82, v82, v50, v52
	v_max3_f32 v82, v82, v53, v70
	v_max3_f32 v83, v83, v72, v73
	v_max3_f32 v82, v82, v71, v54
	v_max3_f32 v83, v83, v56, v57
	v_max3_f32 v82, v82, v55, v74
	v_max3_f32 v83, v83, v76, v77
	v_max3_f32 v82, v82, v75, v58
	v_max3_f32 v83, v83, v60, v61
	v_cndmask_b32_e32 v65, v199, v65, vcc
	v_max3_f32 v82, v82, v59, v78
	v_max3_f32 v83, v83, v80, v81
	v_max3_f32 v82, v82, v79, v62
	v_max3_f32 v83, v83, v64, v65
	v_max3_f32 v82, v82, v63, v83
	v_mov_b32_e32 v83, v82
	s_nop 1
	v_permlane32_swap_b32_e32 v82, v83
	s_nop 0
	s_nop 0
	v_max_f32_e32 v82, v82, v83
	v_sub_f32_e32 v82, v82, v208
	v_cmp_lt_f32_e32 vcc, s66, v82
	s_cmp_lg_u64 vcc, 0
	s_cselect_b64 s[6:7], -1, 0
	s_cbranch_vccz .LBB0_1930
	v_max_f32_e32 v82, v82, v82
	v_max_f32_e32 v83, 0, v82
	v_exp_f32_e64 v82, -v83
	s_and_saveexec_b64 s[4:5], s[0:1]
	ds_write_b32 v207, v82 offset:49152
	s_or_b64 exec, exec, s[4:5]
	v_add_f32_e32 v208, v208, v83
	v_mul_f32_e32 v211, v211, v82

.LBB0_1942:
	v_subrev_u32_e32 v215, 27, v212
	v_add_f32_e32 v211, v211, v214
	v_subrev_u32_e32 v214, 59, v212
	v_cmp_le_i32_e32 vcc, v215, v209
	s_nop 1
	v_cndmask_b32_e32 v82, v199, v82, vcc
	v_cmp_lt_i32_e32 vcc, v214, v209
	s_nop 1
	v_cndmask_b32_e32 v99, v199, v99, vcc
	v_cmp_le_i32_e32 vcc, v214, v209
	v_subrev_u32_e32 v214, 26, v212
	s_nop 0
	v_cndmask_b32_e32 v98, v199, v98, vcc
	v_cmp_le_i32_e32 vcc, v214, v209
	v_subrev_u32_e32 v214, 57, v212
	v_max_f32_e32 v215, v98, v98
	v_cndmask_b32_e32 v83, v199, v83, vcc
	v_cmp_le_i32_e32 vcc, v214, v209
	v_subrev_u32_e32 v214, 25, v212
	s_nop 0
	v_cndmask_b32_e32 v100, v199, v100, vcc
	v_cmp_le_i32_e32 vcc, v214, v209
	v_subrev_u32_e32 v214, 56, v212
	s_nop 0
	v_cndmask_b32_e32 v84, v199, v84, vcc
	v_cmp_le_i32_e32 vcc, v214, v209
	v_subrev_u32_e32 v214, 24, v212
	s_nop 0
	v_cndmask_b32_e32 v101, v199, v101, vcc
	v_cmp_le_i32_e32 vcc, v214, v209
	v_subrev_u32_e32 v214, 51, v212
	s_nop 0
	v_cndmask_b32_e32 v85, v199, v85, vcc
	v_cmp_le_i32_e32 vcc, v214, v209
	v_subrev_u32_e32 v214, 19, v212
	s_nop 0
	v_cndmask_b32_e32 v102, v199, v102, vcc
	v_cmp_le_i32_e32 vcc, v214, v209
	v_subrev_u32_e32 v214, 50, v212
	s_nop 0
	v_cndmask_b32_e32 v86, v199, v86, vcc
	v_cmp_le_i32_e32 vcc, v214, v209
	v_subrev_u32_e32 v214, 18, v212
	s_nop 0
	v_cndmask_b32_e32 v103, v199, v103, vcc
	v_cmp_le_i32_e32 vcc, v214, v209
	v_subrev_u32_e32 v214, 49, v212
	s_nop 0
	v_cndmask_b32_e32 v87, v199, v87, vcc
	v_cmp_le_i32_e32 vcc, v214, v209
	v_subrev_u32_e32 v214, 17, v212
	s_nop 0
	v_cndmask_b32_e32 v104, v199, v104, vcc
	v_cmp_le_i32_e32 vcc, v214, v209
	v_subrev_u32_e32 v214, 48, v212
	s_nop 0
	v_cndmask_b32_e32 v88, v199, v88, vcc
	v_cmp_le_i32_e32 vcc, v214, v209
	v_add_u32_e32 v214, -16, v212
	s_nop 0
	v_cndmask_b32_e32 v105, v199, v105, vcc
	v_cmp_le_i32_e32 vcc, v214, v209
	v_subrev_u32_e32 v214, 43, v212
	s_nop 0
	v_cndmask_b32_e32 v89, v199, v89, vcc
	v_cmp_le_i32_e32 vcc, v214, v209
	v_add_u32_e32 v214, -11, v212
	s_nop 0
	v_cndmask_b32_e32 v106, v199, v106, vcc
	v_cmp_le_i32_e32 vcc, v214, v209
	v_subrev_u32_e32 v214, 42, v212
	s_nop 0
	v_cndmask_b32_e32 v90, v199, v90, vcc
	v_cmp_le_i32_e32 vcc, v214, v209
	v_add_u32_e32 v214, -10, v212
	s_nop 0
	v_cndmask_b32_e32 v107, v199, v107, vcc
	v_cmp_le_i32_e32 vcc, v214, v209
	v_subrev_u32_e32 v214, 41, v212
	s_nop 0
	v_cndmask_b32_e32 v91, v199, v91, vcc
	v_cmp_le_i32_e32 vcc, v214, v209
	v_add_u32_e32 v214, -9, v212
	s_nop 0
	v_cndmask_b32_e32 v108, v199, v108, vcc
	v_cmp_le_i32_e32 vcc, v214, v209
	v_subrev_u32_e32 v214, 40, v212
	s_nop 0
	v_cndmask_b32_e32 v92, v199, v92, vcc
	v_cmp_le_i32_e32 vcc, v214, v209
	v_add_u32_e32 v214, -8, v212
	s_nop 0
	v_cndmask_b32_e32 v109, v199, v109, vcc
	v_cmp_le_i32_e32 vcc, v214, v209
	v_subrev_u32_e32 v214, 35, v212
	s_nop 0
	v_cndmask_b32_e32 v93, v199, v93, vcc
	v_cmp_le_i32_e32 vcc, v214, v209
	v_add_u32_e32 v214, -3, v212
	s_nop 0
	v_cndmask_b32_e32 v110, v199, v110, vcc
	v_cmp_le_i32_e32 vcc, v214, v209
	v_subrev_u32_e32 v214, 34, v212
	s_nop 0
	v_cndmask_b32_e32 v94, v199, v94, vcc
	v_cmp_le_i32_e32 vcc, v214, v209
	v_add_u32_e32 v214, -2, v212
	s_nop 0
	v_cndmask_b32_e32 v111, v199, v111, vcc
	v_cmp_le_i32_e32 vcc, v214, v209
	v_subrev_u32_e32 v214, 33, v212
	s_nop 0
	v_cndmask_b32_e32 v95, v199, v95, vcc
	v_cmp_le_i32_e32 vcc, v214, v209
	v_add_u32_e32 v214, -1, v212
	s_nop 0
	v_cndmask_b32_e32 v112, v199, v112, vcc
	v_cmp_le_i32_e32 vcc, v214, v209
	v_subrev_u32_e32 v214, 32, v212
	s_nop 0
	v_cndmask_b32_e32 v96, v199, v96, vcc
	v_cmp_le_i32_e32 vcc, v214, v209
	v_max_f32_e32 v214, v99, v99
	v_max_f32_e32 v214, v215, v214
	v_max3_f32 v215, v100, v101, v83
	v_max3_f32 v214, v214, v82, v84
	v_max3_f32 v214, v214, v85, v102
	v_max3_f32 v215, v215, v104, v105
	v_max3_f32 v214, v214, v103, v86
	v_max3_f32 v215, v215, v88, v89
	v_max3_f32 v214, v214, v87, v106
	v_max3_f32 v215, v215, v108, v109
	v_cndmask_b32_e32 v113, v199, v113, vcc
	v_cmp_le_i32_e32 vcc, v212, v209
	v_max3_f32 v214, v214, v107, v90
	v_max3_f32 v215, v215, v92, v93
	v_cndmask_b32_e32 v97, v199, v97, vcc
	v_max3_f32 v214, v214, v91, v110
	v_max3_f32 v215, v215, v112, v113
	v_max3_f32 v214, v214, v111, v94
	v_max3_f32 v215, v215, v96, v97
	v_max3_f32 v214, v214, v95, v215
	v_mov_b32_e32 v215, v214
	s_nop 1
	v_permlane32_swap_b32_e32 v214, v215
	s_nop 0
	s_nop 0
	v_max_f32_e32 v214, v214, v215
	v_sub_f32_e32 v214, v214, v208
	v_cmp_lt_f32_e32 vcc, s66, v214
	s_cmp_lg_u64 vcc, 0
	s_cselect_b64 s[38:39], -1, 0
	s_cbranch_vccz .LBB0_1946
	v_max_f32_e32 v214, v214, v214
	v_max_f32_e32 v215, 0, v214
	v_exp_f32_e64 v214, -v215
	s_and_saveexec_b64 s[4:5], s[0:1]
	ds_write_b32 v207, v214 offset:49152
	s_or_b64 exec, exec, s[4:5]
	v_add_f32_e32 v208, v208, v215
	v_mul_f32_e32 v211, v211, v214

.LBB0_1971:
	v_add_u32_e32 v2, s84, v206
	ds_read_b64_tr_b16 v[178:179], v2 offset:24576
	ds_read_b64_tr_b16 v[180:181], v2 offset:25088
	s_waitcnt lgkmcnt(4)
	v_mfma_f32_32x32x16_bf16 v[66:81], v[174:177], v[126:129], v[66:81]
	v_add_f32_e32 v4, v98, v99
	v_add_f32_e32 v4, v100, v4
	v_add_f32_e32 v4, v101, v4
	v_add_f32_e32 v4, v102, v4
	v_add_f32_e32 v4, v103, v4
	v_cvt_pk_bf16_f32 v142, v98, v99
	v_cvt_pk_bf16_f32 v143, v100, v101
	ds_read_b64_tr_b16 v[174:175], v2 offset:28672
	ds_read_b64_tr_b16 v[176:177], v2 offset:29184
	s_waitcnt lgkmcnt(4)
	v_mfma_f32_32x32x16_bf16 v[50:65], v[170:173], v[126:129], v[50:65]
	v_add_f32_e32 v4, v104, v4
	v_add_f32_e32 v4, v105, v4
	v_add_f32_e32 v4, v106, v4
	v_add_f32_e32 v4, v107, v4
	v_cvt_pk_bf16_f32 v144, v102, v103
	v_cvt_pk_bf16_f32 v145, v104, v105
	ds_read_b64_tr_b16 v[126:127], v2 offset:25600
	ds_read_b64_tr_b16 v[128:129], v2 offset:26112
	v_mfma_f32_32x32x16_bf16 v[66:81], v[166:169], v[122:125], v[66:81]
	v_add_f32_e32 v4, v108, v4
	v_add_f32_e32 v4, v109, v4
	v_add_f32_e32 v4, v110, v4
	v_add_f32_e32 v4, v111, v4
	v_cvt_pk_bf16_f32 v138, v106, v107
	v_cvt_pk_bf16_f32 v139, v108, v109
	ds_read_b64_tr_b16 v[102:103], v2 offset:29696
	ds_read_b64_tr_b16 v[104:105], v2 offset:30208
	v_mfma_f32_32x32x16_bf16 v[50:65], v[162:165], v[122:125], v[50:65]
	v_add_f32_e32 v4, v112, v4
	v_add_f32_e32 v4, v113, v4
	v_add_f32_e32 v4, v82, v4
	v_add_f32_e32 v4, v83, v4
	v_cvt_pk_bf16_f32 v140, v110, v111
	v_cvt_pk_bf16_f32 v141, v112, v113
	ds_read_b64_tr_b16 v[98:99], v2 offset:26624
	ds_read_b64_tr_b16 v[100:101], v2 offset:27136
	v_mfma_f32_32x32x16_bf16 v[66:81], v[158:161], v[118:121], v[66:81]
	v_add_f32_e32 v4, v84, v4
	v_add_f32_e32 v4, v85, v4
	v_add_f32_e32 v4, v86, v4
	v_add_f32_e32 v4, v87, v4
	v_cvt_pk_bf16_f32 v134, v82, v83
	v_cvt_pk_bf16_f32 v135, v84, v85
	ds_read_b64_tr_b16 v[12:13], v2 offset:30720
	ds_read_b64_tr_b16 v[14:15], v2 offset:31232
	v_mfma_f32_32x32x16_bf16 v[50:65], v[154:157], v[118:121], v[50:65]
	v_add_f32_e32 v4, v88, v4
	v_add_f32_e32 v4, v89, v4
	v_add_f32_e32 v4, v90, v4
	v_add_f32_e32 v4, v91, v4
	v_cvt_pk_bf16_f32 v136, v86, v87
	v_cvt_pk_bf16_f32 v137, v88, v89
	ds_read_b64_tr_b16 v[8:9], v2 offset:27648
	ds_read_b64_tr_b16 v[10:11], v2 offset:28160
	v_mfma_f32_32x32x16_bf16 v[66:81], v[150:153], v[114:117], v[66:81]
	v_add_f32_e32 v4, v92, v4
	v_add_f32_e32 v4, v93, v4
	v_add_f32_e32 v4, v94, v4
	v_add_f32_e32 v16, v95, v4
	v_cvt_pk_bf16_f32 v130, v90, v91
	v_cvt_pk_bf16_f32 v131, v92, v93
	ds_read_b64_tr_b16 v[4:5], v2 offset:31744
	ds_read_b64_tr_b16 v[6:7], v2 offset:32256
	v_mfma_f32_32x32x16_bf16 v[50:65], v[146:149], v[114:117], v[50:65]
	v_add_f32_e32 v2, v96, v16
	v_add_f32_e32 v2, v97, v2
	s_nop 0
	v_cvt_pk_bf16_f32 v132, v94, v95
	v_cvt_pk_bf16_f32 v133, v96, v97
	v_or_b32_e32 v16, 0xe0, v205
	v_or_b32_e32 v17, 0xc0, v205
	v_cmp_le_i32_e32 vcc, v16, v209
	v_add_f32_e32 v2, v211, v2
	s_nop 3
	v_cndmask_b32_e32 v16, v199, v50, vcc
	v_cmp_lt_i32_e32 vcc, v17, v209
	s_nop 1
	v_cndmask_b32_e32 v50, v199, v67, vcc
	v_cmp_le_i32_e32 vcc, v17, v209
	v_or_b32_e32 v17, 0xe1, v205
	v_or_b32_e32 v67, 0xe2, v205
	v_cndmask_b32_e32 v66, v199, v66, vcc
	v_cmp_le_i32_e32 vcc, v17, v209
	s_nop 1
	v_cndmask_b32_e32 v17, v199, v51, vcc
	v_or_b32_e32 v51, 0xc2, v205
	v_cmp_le_i32_e32 vcc, v51, v209
	s_nop 1
	v_cndmask_b32_e32 v51, v199, v68, vcc
	v_cmp_le_i32_e32 vcc, v67, v209
	v_or_b32_e32 v67, 0xc3, v205
	v_max_f32_e32 v68, v66, v66
	v_cndmask_b32_e32 v52, v199, v52, vcc
	v_cmp_le_i32_e32 vcc, v67, v209
	v_or_b32_e32 v67, 0xe3, v205
	s_nop 0
	v_cndmask_b32_e32 v69, v199, v69, vcc
	v_cmp_le_i32_e32 vcc, v67, v209
	v_or_b32_e32 v67, 0xc8, v205
	s_nop 0
	v_cndmask_b32_e32 v53, v199, v53, vcc
	v_cmp_le_i32_e32 vcc, v67, v209
	v_or_b32_e32 v67, 0xe8, v205
	s_nop 0
	v_cndmask_b32_e32 v70, v199, v70, vcc
	v_cmp_le_i32_e32 vcc, v67, v209
	v_or_b32_e32 v67, 0xc9, v205
	s_nop 0
	v_cndmask_b32_e32 v54, v199, v54, vcc
	v_cmp_le_i32_e32 vcc, v67, v209
	v_or_b32_e32 v67, 0xe9, v205
	s_nop 0
	v_cndmask_b32_e32 v71, v199, v71, vcc
	v_cmp_le_i32_e32 vcc, v67, v209
	v_or_b32_e32 v67, 0xca, v205
	s_nop 0
	v_cndmask_b32_e32 v55, v199, v55, vcc
	v_cmp_le_i32_e32 vcc, v67, v209
	v_or_b32_e32 v67, 0xea, v205
	s_nop 0
	v_cndmask_b32_e32 v72, v199, v72, vcc
	v_cmp_le_i32_e32 vcc, v67, v209
	v_or_b32_e32 v67, 0xcb, v205
	s_nop 0
	v_cndmask_b32_e32 v56, v199, v56, vcc
	v_cmp_le_i32_e32 vcc, v67, v209
	v_or_b32_e32 v67, 0xeb, v205
	s_nop 0
	v_cndmask_b32_e32 v73, v199, v73, vcc
	v_cmp_le_i32_e32 vcc, v67, v209
	v_or_b32_e32 v67, 0xd0, v205
	s_nop 0
	v_cndmask_b32_e32 v57, v199, v57, vcc
	v_cmp_le_i32_e32 vcc, v67, v209
	v_or_b32_e32 v67, 0xf0, v205
	s_nop 0
	v_cndmask_b32_e32 v74, v199, v74, vcc
	v_cmp_le_i32_e32 vcc, v67, v209
	v_or_b32_e32 v67, 0xd1, v205
	s_nop 0
	v_cndmask_b32_e32 v58, v199, v58, vcc
	v_cmp_le_i32_e32 vcc, v67, v209
	v_or_b32_e32 v67, 0xf1, v205
	s_nop 0
	v_cndmask_b32_e32 v75, v199, v75, vcc
	v_cmp_le_i32_e32 vcc, v67, v209
	v_or_b32_e32 v67, 0xd2, v205
	s_nop 0
	v_cndmask_b32_e32 v59, v199, v59, vcc
	v_cmp_le_i32_e32 vcc, v67, v209
	v_or_b32_e32 v67, 0xf2, v205
	s_nop 0
	v_cndmask_b32_e32 v76, v199, v76, vcc
	v_cmp_le_i32_e32 vcc, v67, v209
	v_or_b32_e32 v67, 0xd3, v205
	s_nop 0
	v_cndmask_b32_e32 v60, v199, v60, vcc
	v_cmp_le_i32_e32 vcc, v67, v209
	v_or_b32_e32 v67, 0xf3, v205
	s_nop 0
	v_cndmask_b32_e32 v77, v199, v77, vcc
	v_cmp_le_i32_e32 vcc, v67, v209
	v_or_b32_e32 v67, 0xd8, v205
	s_nop 0
	v_cndmask_b32_e32 v61, v199, v61, vcc
	v_cmp_le_i32_e32 vcc, v67, v209
	v_or_b32_e32 v67, 0xf8, v205
	s_nop 0
	v_cndmask_b32_e32 v78, v199, v78, vcc
	v_cmp_le_i32_e32 vcc, v67, v209
	v_or_b32_e32 v67, 0xd9, v205
	s_nop 0
	v_cndmask_b32_e32 v62, v199, v62, vcc
	v_cmp_le_i32_e32 vcc, v67, v209
	v_or_b32_e32 v67, 0xf9, v205
	s_nop 0
	v_cndmask_b32_e32 v79, v199, v79, vcc
	v_cmp_le_i32_e32 vcc, v67, v209
	v_or_b32_e32 v67, 0xda, v205
	s_nop 0
	v_cndmask_b32_e32 v63, v199, v63, vcc
	v_cmp_le_i32_e32 vcc, v67, v209
	v_or_b32_e32 v67, 0xfa, v205
	s_nop 0
	v_cndmask_b32_e32 v80, v199, v80, vcc
	v_cmp_le_i32_e32 vcc, v67, v209
	v_or_b32_e32 v67, 0xdb, v205
	s_nop 0
	v_cndmask_b32_e32 v64, v199, v64, vcc
	v_cmp_le_i32_e32 vcc, v67, v209
	v_or_b32_e32 v67, 0xfb, v205
	s_nop 0
	v_cndmask_b32_e32 v81, v199, v81, vcc
	v_cmp_le_i32_e32 vcc, v67, v209
	v_max_f32_e32 v67, v50, v50
	v_max_f32_e32 v67, v68, v67
	v_max3_f32 v68, v51, v69, v17
	v_max3_f32 v67, v67, v16, v52
	v_max3_f32 v67, v67, v53, v70
	v_max3_f32 v68, v68, v72, v73
	v_max3_f32 v67, v67, v71, v54
	v_max3_f32 v68, v68, v56, v57
	v_max3_f32 v67, v67, v55, v74
	v_max3_f32 v68, v68, v76, v77
	v_max3_f32 v67, v67, v75, v58
	v_max3_f32 v68, v68, v60, v61
	v_cndmask_b32_e32 v65, v199, v65, vcc
	v_max3_f32 v67, v67, v59, v78
	v_max3_f32 v68, v68, v80, v81
	v_max3_f32 v67, v67, v79, v62
	v_max3_f32 v68, v68, v64, v65
	v_max3_f32 v67, v67, v63, v68
	v_mov_b32_e32 v68, v67
	s_nop 1
	v_permlane32_swap_b32_e32 v67, v68
	s_nop 0
	s_nop 0
	v_max_f32_e32 v67, v67, v68
	v_sub_f32_e32 v67, v67, v208
	v_cmp_lt_f32_e32 vcc, s66, v67
	s_cmp_lg_u64 vcc, 0
	s_cselect_b64 s[0:1], -1, 0
	s_cbranch_vccz .LBB0_1975
	v_max_f32_e32 v67, v67, v67
	v_max_f32_e32 v68, 0, v67
	v_exp_f32_e64 v67, -v68
	v_cmp_gt_u32_e32 vcc, 32, v202
	s_and_saveexec_b64 s[4:5], vcc
	ds_write_b32 v207, v67 offset:49152
	s_or_b64 exec, exec, s[4:5]
	v_add_f32_e32 v208, v208, v68
	v_mul_f32_e32 v2, v2, v67

.LBB0_1980:
	v_add_u32_e32 v2, s4, v209
	ds_read_b64_tr_b16 v[184:185], v2 offset:24576
	ds_read_b64_tr_b16 v[186:187], v2 offset:25088
	s_waitcnt lgkmcnt(2)
	v_mfma_f32_32x32x16_bf16 v[52:67], v[160:163], v[128:131], v[52:67]
	v_add_f32_e32 v100, v84, v85
	v_add_f32_e32 v100, v86, v100
	v_add_f32_e32 v100, v87, v100
	v_add_f32_e32 v100, v88, v100
	v_add_f32_e32 v100, v89, v100
	v_cvt_pk_bf16_f32 v120, v84, v85
	v_cvt_pk_bf16_f32 v121, v86, v87
	ds_read_b64_tr_b16 v[160:161], v2 offset:28672
	ds_read_b64_tr_b16 v[162:163], v2 offset:29184
	v_mfma_f32_32x32x16_bf16 v[36:51], v[156:159], v[128:131], v[36:51]
	v_add_f32_e32 v84, v90, v100
	v_add_f32_e32 v84, v91, v84
	v_add_f32_e32 v84, v92, v84
	v_add_f32_e32 v84, v93, v84
	v_cvt_pk_bf16_f32 v122, v88, v89
	v_cvt_pk_bf16_f32 v123, v90, v91
	ds_read_b64_tr_b16 v[156:157], v2 offset:25600
	ds_read_b64_tr_b16 v[158:159], v2 offset:26112
	v_mfma_f32_32x32x16_bf16 v[52:67], v[152:155], v[124:127], v[52:67]
	v_add_f32_e32 v84, v94, v84
	v_add_f32_e32 v84, v95, v84
	v_add_f32_e32 v84, v96, v84
	v_add_f32_e32 v84, v97, v84
	v_cvt_pk_bf16_f32 v112, v92, v93
	v_cvt_pk_bf16_f32 v113, v94, v95
	ds_read_b64_tr_b16 v[180:181], v2 offset:29696
	ds_read_b64_tr_b16 v[182:183], v2 offset:30208
	v_mfma_f32_32x32x16_bf16 v[36:51], v[148:151], v[124:127], v[36:51]
	v_add_f32_e32 v84, v98, v84
	v_add_f32_e32 v84, v99, v84
	v_add_f32_e32 v84, v68, v84
	v_add_f32_e32 v84, v69, v84
	v_cvt_pk_bf16_f32 v114, v96, v97
	v_cvt_pk_bf16_f32 v115, v98, v99
	ds_read_b64_tr_b16 v[176:177], v2 offset:26624
	ds_read_b64_tr_b16 v[178:179], v2 offset:27136
	v_mfma_f32_32x32x16_bf16 v[52:67], v[144:147], v[116:119], v[52:67]
	v_add_f32_e32 v84, v70, v84
	v_add_f32_e32 v84, v71, v84
	v_add_f32_e32 v84, v72, v84
	v_add_f32_e32 v84, v73, v84
	v_cvt_pk_bf16_f32 v104, v68, v69
	v_cvt_pk_bf16_f32 v105, v70, v71
	ds_read_b64_tr_b16 v[172:173], v2 offset:30720
	ds_read_b64_tr_b16 v[174:175], v2 offset:31232
	v_mfma_f32_32x32x16_bf16 v[36:51], v[140:143], v[116:119], v[36:51]
	v_add_f32_e32 v68, v74, v84
	v_add_f32_e32 v68, v75, v68
	v_add_f32_e32 v68, v76, v68
	v_add_f32_e32 v68, v77, v68
	v_cvt_pk_bf16_f32 v106, v72, v73
	v_cvt_pk_bf16_f32 v107, v74, v75
	ds_read_b64_tr_b16 v[168:169], v2 offset:27648
	ds_read_b64_tr_b16 v[170:171], v2 offset:28160
	v_mfma_f32_32x32x16_bf16 v[52:67], v[136:139], v[108:111], v[52:67]
	v_add_f32_e32 v68, v78, v68
	v_add_f32_e32 v68, v79, v68
	v_add_f32_e32 v68, v80, v68
	v_add_f32_e32 v68, v81, v68
	v_cvt_pk_bf16_f32 v100, v76, v77
	v_cvt_pk_bf16_f32 v101, v78, v79
	ds_read_b64_tr_b16 v[164:165], v2 offset:31744
	ds_read_b64_tr_b16 v[166:167], v2 offset:32256
	v_mfma_f32_32x32x16_bf16 v[36:51], v[132:135], v[108:111], v[36:51]
	v_add_f32_e32 v2, v82, v68
	v_add_f32_e32 v2, v83, v2
	s_nop 0
	v_cvt_pk_bf16_f32 v102, v80, v81
	v_cvt_pk_bf16_f32 v103, v82, v83
	v_lshl_add_u64 v[68:69], v[190:191], 0, s[18:19]
	s_add_i32 s4, s27, s37
	s_mov_b32 s5, m0
	s_mov_b32 m0, s4
	s_nop 0
	global_load_lds_dwordx4 v[68:69], off
	s_mov_b32 m0, s5
	v_lshl_add_u64 v[68:69], v[188:189], 0, s[18:19]
	v_add_f32_e32 v194, v214, v2
	s_add_i32 s4, s7, s38
	s_mov_b32 s5, m0
	s_mov_b32 m0, s4
	s_nop 0
	global_load_lds_dwordx4 v[68:69], off
	s_mov_b32 m0, s5
	s_nop 0
	s_nop 0
	v_max_f32_e32 v2, v52, v53
	v_max3_f32 v68, v54, v55, v37
	v_max3_f32 v2, v2, v36, v38
	v_max3_f32 v2, v2, v39, v56
	v_max3_f32 v68, v68, v58, v59
	v_max3_f32 v2, v2, v57, v40
	v_max3_f32 v68, v68, v42, v43
	v_max3_f32 v2, v2, v41, v60
	v_max3_f32 v68, v68, v62, v63
	v_max3_f32 v2, v2, v61, v44
	v_max3_f32 v68, v68, v46, v47
	v_max3_f32 v2, v2, v45, v64
	v_max3_f32 v68, v68, v66, v67
	v_max3_f32 v2, v2, v65, v48
	v_max3_f32 v68, v68, v50, v51
	v_max3_f32 v2, v2, v49, v68
	v_mov_b32_e32 v68, v2
	s_nop 1
	v_permlane32_swap_b32_e32 v2, v68
	s_nop 0
	s_nop 0
	v_max_f32_e32 v2, v2, v68
	v_sub_f32_e32 v2, v2, v210
	v_cmp_lt_f32_e32 vcc, s66, v2
	s_cmp_lg_u64 vcc, 0
	s_cselect_b64 s[22:23], -1, 0
	s_cbranch_vccz .LBB0_1984
	v_max_f32_e32 v2, v2, v2
	v_max_f32_e32 v68, 0, v2
	v_exp_f32_e64 v2, -v68
	s_and_saveexec_b64 s[4:5], s[0:1]
	ds_write_b32 v207, v2 offset:49152
	s_or_b64 exec, exec, s[4:5]
	v_add_f32_e32 v210, v210, v68
	v_mul_f32_e32 v194, v194, v2

.LBB0_1986:
	s_add_i32 s4, s7, 0x2000
	s_cmpk_lg_i32 s7, 0x4000
	s_cselect_b32 s58, s4, 0
	v_add_u32_e32 v166, s27, v209
	ds_read_b64_tr_b16 v[184:185], v166 offset:24576
	ds_read_b64_tr_b16 v[186:187], v166 offset:25088
	s_waitcnt lgkmcnt(9)
	v_mfma_f32_32x32x16_bf16 v[84:99], v[160:163], v[128:131], v[84:99]
	v_add_f32_e32 v100, v52, v53
	v_add_f32_e32 v100, v54, v100
	v_add_f32_e32 v100, v55, v100
	v_add_f32_e32 v100, v56, v100
	v_add_f32_e32 v100, v57, v100
	v_cvt_pk_bf16_f32 v120, v52, v53
	v_cvt_pk_bf16_f32 v121, v54, v55
	ds_read_b64_tr_b16 v[160:161], v166 offset:28672
	ds_read_b64_tr_b16 v[162:163], v166 offset:29184
	s_waitcnt lgkmcnt(10)
	v_mfma_f32_32x32x16_bf16 v[68:83], v[152:155], v[128:131], v[68:83]
	v_add_f32_e32 v52, v58, v100
	v_add_f32_e32 v52, v59, v52
	v_add_f32_e32 v52, v60, v52
	v_add_f32_e32 v52, v61, v52
	v_cvt_pk_bf16_f32 v122, v56, v57
	v_cvt_pk_bf16_f32 v123, v58, v59
	ds_read_b64_tr_b16 v[152:153], v166 offset:25600
	ds_read_b64_tr_b16 v[154:155], v166 offset:26112
	s_waitcnt lgkmcnt(11)
	v_mfma_f32_32x32x16_bf16 v[84:99], v[156:159], v[124:127], v[84:99]
	v_add_f32_e32 v52, v62, v52
	v_add_f32_e32 v52, v63, v52
	v_add_f32_e32 v52, v64, v52
	v_add_f32_e32 v52, v65, v52
	v_cvt_pk_bf16_f32 v112, v60, v61
	v_cvt_pk_bf16_f32 v113, v62, v63
	ds_read_b64_tr_b16 v[180:181], v166 offset:29696
	ds_read_b64_tr_b16 v[182:183], v166 offset:30208
	s_waitcnt lgkmcnt(12)
	v_mfma_f32_32x32x16_bf16 v[68:83], v[144:147], v[124:127], v[68:83]
	v_add_f32_e32 v52, v66, v52
	v_add_f32_e32 v52, v67, v52
	v_add_f32_e32 v52, v36, v52
	v_add_f32_e32 v52, v37, v52
	v_cvt_pk_bf16_f32 v114, v64, v65
	v_cvt_pk_bf16_f32 v115, v66, v67
	ds_read_b64_tr_b16 v[176:177], v166 offset:26624
	ds_read_b64_tr_b16 v[178:179], v166 offset:27136
	s_waitcnt lgkmcnt(13)
	v_mfma_f32_32x32x16_bf16 v[84:99], v[148:151], v[116:119], v[84:99]
	v_add_f32_e32 v52, v38, v52
	v_add_f32_e32 v52, v39, v52
	v_add_f32_e32 v52, v40, v52
	v_add_f32_e32 v52, v41, v52
	v_cvt_pk_bf16_f32 v104, v36, v37
	v_cvt_pk_bf16_f32 v105, v38, v39
	ds_read_b64_tr_b16 v[172:173], v166 offset:30720
	ds_read_b64_tr_b16 v[174:175], v166 offset:31232
	s_waitcnt lgkmcnt(14)
	v_mfma_f32_32x32x16_bf16 v[68:83], v[136:139], v[116:119], v[68:83]
	v_add_f32_e32 v36, v42, v52
	v_add_f32_e32 v36, v43, v36
	v_add_f32_e32 v36, v44, v36
	v_add_f32_e32 v36, v45, v36
	v_cvt_pk_bf16_f32 v106, v40, v41
	v_cvt_pk_bf16_f32 v107, v42, v43
	ds_read_b64_tr_b16 v[168:169], v166 offset:27648
	ds_read_b64_tr_b16 v[170:171], v166 offset:28160
	s_waitcnt lgkmcnt(14)
	v_mfma_f32_32x32x16_bf16 v[84:99], v[140:143], v[108:111], v[84:99]
	v_add_f32_e32 v36, v46, v36
	v_add_f32_e32 v36, v47, v36
	v_add_f32_e32 v36, v48, v36
	v_add_f32_e32 v36, v49, v36
	v_cvt_pk_bf16_f32 v100, v44, v45
	v_cvt_pk_bf16_f32 v101, v46, v47
	ds_read_b64_tr_b16 v[164:165], v166 offset:31744
	ds_read_b64_tr_b16 v[166:167], v166 offset:32256
	v_mfma_f32_32x32x16_bf16 v[68:83], v[132:135], v[108:111], v[68:83]
	v_add_f32_e32 v36, v50, v36
	v_add_f32_e32 v36, v51, v36
	s_nop 0
	v_cvt_pk_bf16_f32 v102, v48, v49
	v_cvt_pk_bf16_f32 v103, v50, v51
	s_nop 0
	v_add_f32_e32 v214, v194, v36
	s_nop 0
	s_nop 0
	v_max_f32_e32 v36, v84, v85
	s_nop 2
	v_max3_f32 v37, v86, v87, v69
	v_max3_f32 v36, v36, v68, v70
	v_max3_f32 v36, v36, v71, v88
	v_max3_f32 v37, v37, v90, v91
	v_max3_f32 v36, v36, v89, v72
	v_max3_f32 v37, v37, v74, v75
	v_max3_f32 v36, v36, v73, v92
	v_max3_f32 v37, v37, v94, v95
	v_max3_f32 v36, v36, v93, v76
	v_max3_f32 v37, v37, v78, v79
	v_max3_f32 v36, v36, v77, v96
	v_max3_f32 v37, v37, v98, v99
	v_max3_f32 v36, v36, v97, v80
	v_max3_f32 v37, v37, v82, v83
	v_max3_f32 v36, v36, v81, v37
	v_mov_b32_e32 v37, v36
	s_nop 1
	v_permlane32_swap_b32_e32 v36, v37
	s_nop 0
	s_nop 0
	v_max_f32_e32 v36, v36, v37
	s_add_i32 s4, s7, s37
	s_mov_b32 s5, m0
	s_mov_b32 m0, s4
	s_nop 0
	global_load_lds_dwordx4 v[190:191], off
	s_mov_b32 m0, s5
	v_sub_f32_e32 v36, v36, v210
	s_add_i32 s4, s58, s38
	s_mov_b32 s5, m0
	s_mov_b32 m0, s4
	s_nop 0
	global_load_lds_dwordx4 v[188:189], off
	s_mov_b32 m0, s5
	v_cmp_lt_f32_e32 vcc, s66, v36
	s_cmp_lg_u64 vcc, 0
	s_cselect_b64 s[22:23], -1, 0
	s_cbranch_vccz .LBB0_1990
	v_max_f32_e32 v36, v36, v36
	v_max_f32_e32 v37, 0, v36
	v_exp_f32_e64 v36, -v37
	s_and_saveexec_b64 s[4:5], s[0:1]
	ds_write_b32 v207, v36 offset:49152
	s_or_b64 exec, exec, s[4:5]
	v_add_f32_e32 v210, v210, v37
	v_mul_f32_e32 v214, v214, v36

.LBB0_1998:
	v_add_u32_e32 v166, s7, v209
	ds_read_b64_tr_b16 v[188:189], v166 offset:24576
	ds_read_b64_tr_b16 v[190:191], v166 offset:25088
	s_waitcnt lgkmcnt(9)
	v_mfma_f32_32x32x16_bf16 v[52:67], v[160:163], v[128:131], v[52:67]
	v_add_f32_e32 v100, v84, v85
	v_add_f32_e32 v100, v86, v100
	v_add_f32_e32 v100, v87, v100
	v_add_f32_e32 v100, v88, v100
	v_add_f32_e32 v100, v89, v100
	v_cvt_pk_bf16_f32 v120, v84, v85
	v_cvt_pk_bf16_f32 v121, v86, v87
	ds_read_b64_tr_b16 v[160:161], v166 offset:28672
	ds_read_b64_tr_b16 v[162:163], v166 offset:29184
	s_waitcnt lgkmcnt(10)
	v_mfma_f32_32x32x16_bf16 v[36:51], v[156:159], v[128:131], v[36:51]
	v_add_f32_e32 v84, v90, v100
	v_add_f32_e32 v84, v91, v84
	v_add_f32_e32 v84, v92, v84
	v_add_f32_e32 v84, v93, v84
	v_cvt_pk_bf16_f32 v122, v88, v89
	v_cvt_pk_bf16_f32 v123, v90, v91
	ds_read_b64_tr_b16 v[184:185], v166 offset:25600
	ds_read_b64_tr_b16 v[186:187], v166 offset:26112
	s_waitcnt lgkmcnt(11)
	v_mfma_f32_32x32x16_bf16 v[52:67], v[152:155], v[124:127], v[52:67]
	v_add_f32_e32 v84, v94, v84
	v_add_f32_e32 v84, v95, v84
	v_add_f32_e32 v84, v96, v84
	v_add_f32_e32 v84, v97, v84
	v_cvt_pk_bf16_f32 v112, v92, v93
	v_cvt_pk_bf16_f32 v113, v94, v95
	ds_read_b64_tr_b16 v[180:181], v166 offset:29696
	ds_read_b64_tr_b16 v[182:183], v166 offset:30208
	s_waitcnt lgkmcnt(12)
	v_mfma_f32_32x32x16_bf16 v[36:51], v[148:151], v[124:127], v[36:51]
	v_add_f32_e32 v84, v98, v84
	v_add_f32_e32 v84, v99, v84
	v_add_f32_e32 v84, v68, v84
	v_add_f32_e32 v84, v69, v84
	v_cvt_pk_bf16_f32 v114, v96, v97
	v_cvt_pk_bf16_f32 v115, v98, v99
	ds_read_b64_tr_b16 v[176:177], v166 offset:26624
	ds_read_b64_tr_b16 v[178:179], v166 offset:27136
	s_waitcnt lgkmcnt(13)
	v_mfma_f32_32x32x16_bf16 v[52:67], v[144:147], v[116:119], v[52:67]
	v_add_f32_e32 v84, v70, v84
	v_add_f32_e32 v84, v71, v84
	v_add_f32_e32 v84, v72, v84
	v_add_f32_e32 v84, v73, v84
	v_cvt_pk_bf16_f32 v104, v68, v69
	v_cvt_pk_bf16_f32 v105, v70, v71
	ds_read_b64_tr_b16 v[172:173], v166 offset:30720
	ds_read_b64_tr_b16 v[174:175], v166 offset:31232
	s_waitcnt lgkmcnt(14)
	v_mfma_f32_32x32x16_bf16 v[36:51], v[140:143], v[116:119], v[36:51]
	v_add_f32_e32 v68, v74, v84
	v_add_f32_e32 v68, v75, v68
	v_add_f32_e32 v68, v76, v68
	v_add_f32_e32 v68, v77, v68
	v_cvt_pk_bf16_f32 v106, v72, v73
	v_cvt_pk_bf16_f32 v107, v74, v75
	ds_read_b64_tr_b16 v[168:169], v166 offset:27648
	ds_read_b64_tr_b16 v[170:171], v166 offset:28160
	s_waitcnt lgkmcnt(14)
	v_mfma_f32_32x32x16_bf16 v[52:67], v[136:139], v[108:111], v[52:67]
	v_add_f32_e32 v68, v78, v68
	v_add_f32_e32 v68, v79, v68
	v_add_f32_e32 v68, v80, v68
	v_add_f32_e32 v68, v81, v68
	v_cvt_pk_bf16_f32 v100, v76, v77
	v_cvt_pk_bf16_f32 v101, v78, v79
	ds_read_b64_tr_b16 v[164:165], v166 offset:31744
	ds_read_b64_tr_b16 v[166:167], v166 offset:32256
	v_mfma_f32_32x32x16_bf16 v[36:51], v[132:135], v[108:111], v[36:51]
	v_add_f32_e32 v68, v82, v68
	v_add_f32_e32 v68, v83, v68
	s_nop 0
	v_cvt_pk_bf16_f32 v102, v80, v81
	v_cvt_pk_bf16_f32 v103, v82, v83
	s_add_i32 s8, s6, 1
	s_cmp_ge_u32 s8, s36
	s_cselect_b64 s[22:23], -1, 0
	s_and_b64 vcc, exec, s[22:23]
	s_cbranch_vccnz .LBB0_2000
	s_lshl_b64 s[4:5], s[8:9], 16
	s_add_i32 s7, s58, s37
	v_lshl_add_u64 v[70:71], v[196:197], 0, s[4:5]
	s_mov_b32 s4, m0
	s_mov_b32 m0, s7
	s_nop 0
	global_load_lds_dwordx4 v[70:71], off
	s_mov_b32 m0, s4
.LBB0_2000:
	v_add_f32_e32 v214, v214, v68
	v_add_u32_e32 v68, 32, v212
	v_cmp_le_i32_e32 vcc, v68, v215
	v_add_u32_e32 v68, 33, v212
	s_add_i32 s4, s59, s38
	v_cndmask_b32_e32 v36, v199, v36, vcc
	v_cmp_lt_i32_e32 vcc, v212, v215
	s_mov_b32 s5, m0
	s_mov_b32 m0, s4
	s_nop 0
	global_load_lds_dwordx4 v[202:203], off
	s_mov_b32 m0, s5
	s_nop 1
	v_cndmask_b32_e32 v53, v199, v53, vcc
	v_cmp_le_i32_e32 vcc, v212, v215
	s_nop 1
	v_cndmask_b32_e32 v52, v199, v52, vcc
	v_cmp_le_i32_e32 vcc, v68, v215
	v_add_u32_e32 v68, 2, v212
	v_max_f32_e32 v69, v52, v52
	v_cndmask_b32_e32 v37, v199, v37, vcc
	v_cmp_le_i32_e32 vcc, v68, v215
	v_add_u32_e32 v68, 34, v212
	s_nop 0
	v_cndmask_b32_e32 v54, v199, v54, vcc
	v_cmp_le_i32_e32 vcc, v68, v215
	v_add_u32_e32 v68, 3, v212
	s_nop 0
	v_cndmask_b32_e32 v38, v199, v38, vcc
	v_cmp_le_i32_e32 vcc, v68, v215
	v_add_u32_e32 v68, 35, v212
	s_nop 0
	v_cndmask_b32_e32 v55, v199, v55, vcc
	v_cmp_le_i32_e32 vcc, v68, v215
	v_add_u32_e32 v68, 8, v212
	s_nop 0
	v_cndmask_b32_e32 v39, v199, v39, vcc
	v_cmp_le_i32_e32 vcc, v68, v215
	v_add_u32_e32 v68, 40, v212
	s_nop 0
	v_cndmask_b32_e32 v56, v199, v56, vcc
	v_cmp_le_i32_e32 vcc, v68, v215
	v_add_u32_e32 v68, 9, v212
	s_nop 0
	v_cndmask_b32_e32 v40, v199, v40, vcc
	v_cmp_le_i32_e32 vcc, v68, v215
	v_add_u32_e32 v68, 41, v212
	s_nop 0
	v_cndmask_b32_e32 v57, v199, v57, vcc
	v_cmp_le_i32_e32 vcc, v68, v215
	v_add_u32_e32 v68, 10, v212
	s_nop 0
	v_cndmask_b32_e32 v41, v199, v41, vcc
	v_cmp_le_i32_e32 vcc, v68, v215
	v_add_u32_e32 v68, 42, v212
	s_nop 0
	v_cndmask_b32_e32 v58, v199, v58, vcc
	v_cmp_le_i32_e32 vcc, v68, v215
	v_add_u32_e32 v68, 11, v212
	s_nop 0
	v_cndmask_b32_e32 v42, v199, v42, vcc
	v_cmp_le_i32_e32 vcc, v68, v215
	v_add_u32_e32 v68, 43, v212
	s_nop 0
	v_cndmask_b32_e32 v59, v199, v59, vcc
	v_cmp_le_i32_e32 vcc, v68, v215
	v_add_u32_e32 v68, 16, v212
	s_nop 0
	v_cndmask_b32_e32 v43, v199, v43, vcc
	v_cmp_le_i32_e32 vcc, v68, v215
	v_add_u32_e32 v68, 48, v212
	s_nop 0
	v_cndmask_b32_e32 v60, v199, v60, vcc
	v_cmp_le_i32_e32 vcc, v68, v215
	v_add_u32_e32 v68, 17, v212
	s_nop 0
	v_cndmask_b32_e32 v44, v199, v44, vcc
	v_cmp_le_i32_e32 vcc, v68, v215
	v_add_u32_e32 v68, 49, v212
	s_nop 0
	v_cndmask_b32_e32 v61, v199, v61, vcc
	v_cmp_le_i32_e32 vcc, v68, v215
	v_add_u32_e32 v68, 18, v212
	s_nop 0
	v_cndmask_b32_e32 v45, v199, v45, vcc
	v_cmp_le_i32_e32 vcc, v68, v215
	v_add_u32_e32 v68, 50, v212
	s_nop 0
	v_cndmask_b32_e32 v62, v199, v62, vcc
	v_cmp_le_i32_e32 vcc, v68, v215
	v_add_u32_e32 v68, 19, v212
	s_nop 0
	v_cndmask_b32_e32 v46, v199, v46, vcc
	v_cmp_le_i32_e32 vcc, v68, v215
	v_add_u32_e32 v68, 51, v212
	s_nop 0
	v_cndmask_b32_e32 v63, v199, v63, vcc
	v_cmp_le_i32_e32 vcc, v68, v215
	v_add_u32_e32 v68, 24, v212
	s_nop 0
	v_cndmask_b32_e32 v47, v199, v47, vcc
	v_cmp_le_i32_e32 vcc, v68, v215
	v_add_u32_e32 v68, 56, v212
	s_nop 0
	v_cndmask_b32_e32 v64, v199, v64, vcc
	v_cmp_le_i32_e32 vcc, v68, v215
	v_add_u32_e32 v68, 25, v212
	s_nop 0
	v_cndmask_b32_e32 v48, v199, v48, vcc
	v_cmp_le_i32_e32 vcc, v68, v215
	v_add_u32_e32 v68, 57, v212
	s_nop 0
	v_cndmask_b32_e32 v65, v199, v65, vcc
	v_cmp_le_i32_e32 vcc, v68, v215
	v_add_u32_e32 v68, 26, v212
	s_nop 0
	v_cndmask_b32_e32 v49, v199, v49, vcc
	v_cmp_le_i32_e32 vcc, v68, v215
	v_add_u32_e32 v68, 58, v212
	s_nop 0
	v_cndmask_b32_e32 v66, v199, v66, vcc
	v_cmp_le_i32_e32 vcc, v68, v215
	v_add_u32_e32 v68, 27, v212
	s_nop 0
	v_cndmask_b32_e32 v50, v199, v50, vcc
	v_cmp_le_i32_e32 vcc, v68, v215
	v_add_u32_e32 v68, 59, v212
	s_nop 0
	v_cndmask_b32_e32 v67, v199, v67, vcc
	v_cmp_le_i32_e32 vcc, v68, v215
	v_max_f32_e32 v68, v53, v53
	v_max_f32_e32 v68, v69, v68
	v_max3_f32 v69, v54, v55, v37
	v_max3_f32 v68, v68, v36, v38
	v_max3_f32 v68, v68, v39, v56
	v_max3_f32 v69, v69, v58, v59
	v_max3_f32 v68, v68, v57, v40
	v_max3_f32 v69, v69, v42, v43
	v_max3_f32 v68, v68, v41, v60
	v_max3_f32 v69, v69, v62, v63
	v_max3_f32 v68, v68, v61, v44
	v_max3_f32 v69, v69, v46, v47
	v_cndmask_b32_e32 v51, v199, v51, vcc
	v_max3_f32 v68, v68, v45, v64
	v_max3_f32 v69, v69, v66, v67
	v_max3_f32 v68, v68, v65, v48
	v_max3_f32 v69, v69, v50, v51
	v_max3_f32 v68, v68, v49, v69
	v_mov_b32_e32 v69, v68
	s_nop 1
	v_permlane32_swap_b32_e32 v68, v69
	s_nop 0
	s_nop 0
	v_max_f32_e32 v68, v68, v69
	v_sub_f32_e32 v68, v68, v210
	v_cmp_lt_f32_e32 vcc, s66, v68
	s_cmp_lg_u64 vcc, 0
	s_cselect_b64 s[26:27], -1, 0
	s_cbranch_vccz .LBB0_2004
	v_max_f32_e32 v68, v68, v68
	v_max_f32_e32 v69, 0, v68
	v_exp_f32_e64 v68, -v69
	s_and_saveexec_b64 s[4:5], s[0:1]
	ds_write_b32 v207, v68 offset:49152
	s_or_b64 exec, exec, s[4:5]
	v_add_f32_e32 v210, v210, v69
	v_mul_f32_e32 v214, v214, v68

.LBB0_2016:
	v_add_u32_e32 v217, 0x60, v212
	v_add_f32_e32 v214, v214, v216
	v_add_u32_e32 v216, 64, v212
	v_cmp_le_i32_e32 vcc, v217, v215
	s_nop 1
	v_cndmask_b32_e32 v68, v199, v68, vcc
	v_cmp_lt_i32_e32 vcc, v216, v215
	s_nop 1
	v_cndmask_b32_e32 v85, v199, v85, vcc
	v_cmp_le_i32_e32 vcc, v216, v215
	v_add_u32_e32 v216, 0x61, v212
	s_nop 0
	v_cndmask_b32_e32 v84, v199, v84, vcc
	v_cmp_le_i32_e32 vcc, v216, v215
	v_add_u32_e32 v216, 0x42, v212
	v_max_f32_e32 v217, v84, v84
	v_cndmask_b32_e32 v69, v199, v69, vcc
	v_cmp_le_i32_e32 vcc, v216, v215
	v_add_u32_e32 v216, 0x62, v212
	s_nop 0
	v_cndmask_b32_e32 v86, v199, v86, vcc
	v_cmp_le_i32_e32 vcc, v216, v215
	v_add_u32_e32 v216, 0x43, v212
	s_nop 0
	v_cndmask_b32_e32 v70, v199, v70, vcc
	v_cmp_le_i32_e32 vcc, v216, v215
	v_add_u32_e32 v216, 0x63, v212
	s_nop 0
	v_cndmask_b32_e32 v87, v199, v87, vcc
	v_cmp_le_i32_e32 vcc, v216, v215
	v_add_u32_e32 v216, 0x48, v212
	s_nop 0
	v_cndmask_b32_e32 v71, v199, v71, vcc
	v_cmp_le_i32_e32 vcc, v216, v215
	v_add_u32_e32 v216, 0x68, v212
	s_nop 0
	v_cndmask_b32_e32 v88, v199, v88, vcc
	v_cmp_le_i32_e32 vcc, v216, v215
	v_add_u32_e32 v216, 0x49, v212
	s_nop 0
	v_cndmask_b32_e32 v72, v199, v72, vcc
	v_cmp_le_i32_e32 vcc, v216, v215
	v_add_u32_e32 v216, 0x69, v212
	s_nop 0
	v_cndmask_b32_e32 v89, v199, v89, vcc
	v_cmp_le_i32_e32 vcc, v216, v215
	v_add_u32_e32 v216, 0x4a, v212
	s_nop 0
	v_cndmask_b32_e32 v73, v199, v73, vcc
	v_cmp_le_i32_e32 vcc, v216, v215
	v_add_u32_e32 v216, 0x6a, v212
	s_nop 0
	v_cndmask_b32_e32 v90, v199, v90, vcc
	v_cmp_le_i32_e32 vcc, v216, v215
	v_add_u32_e32 v216, 0x4b, v212
	s_nop 0
	v_cndmask_b32_e32 v74, v199, v74, vcc
	v_cmp_le_i32_e32 vcc, v216, v215
	v_add_u32_e32 v216, 0x6b, v212
	s_nop 0
	v_cndmask_b32_e32 v91, v199, v91, vcc
	v_cmp_le_i32_e32 vcc, v216, v215
	v_add_u32_e32 v216, 0x50, v212
	s_nop 0
	v_cndmask_b32_e32 v75, v199, v75, vcc
	v_cmp_le_i32_e32 vcc, v216, v215
	v_add_u32_e32 v216, 0x70, v212
	s_nop 0
	v_cndmask_b32_e32 v92, v199, v92, vcc
	v_cmp_le_i32_e32 vcc, v216, v215
	v_add_u32_e32 v216, 0x51, v212
	s_nop 0
	v_cndmask_b32_e32 v76, v199, v76, vcc
	v_cmp_le_i32_e32 vcc, v216, v215
	v_add_u32_e32 v216, 0x71, v212
	s_nop 0
	v_cndmask_b32_e32 v93, v199, v93, vcc
	v_cmp_le_i32_e32 vcc, v216, v215
	v_add_u32_e32 v216, 0x52, v212
	s_nop 0
	v_cndmask_b32_e32 v77, v199, v77, vcc
	v_cmp_le_i32_e32 vcc, v216, v215
	v_add_u32_e32 v216, 0x72, v212
	s_nop 0
	v_cndmask_b32_e32 v94, v199, v94, vcc
	v_cmp_le_i32_e32 vcc, v216, v215
	v_add_u32_e32 v216, 0x53, v212
	s_nop 0
	v_cndmask_b32_e32 v78, v199, v78, vcc
	v_cmp_le_i32_e32 vcc, v216, v215
	v_add_u32_e32 v216, 0x73, v212
	s_nop 0
	v_cndmask_b32_e32 v95, v199, v95, vcc
	v_cmp_le_i32_e32 vcc, v216, v215
	v_add_u32_e32 v216, 0x58, v212
	s_nop 0
	v_cndmask_b32_e32 v79, v199, v79, vcc
	v_cmp_le_i32_e32 vcc, v216, v215
	v_add_u32_e32 v216, 0x78, v212
	s_nop 0
	v_cndmask_b32_e32 v96, v199, v96, vcc
	v_cmp_le_i32_e32 vcc, v216, v215
	v_add_u32_e32 v216, 0x59, v212
	s_nop 0
	v_cndmask_b32_e32 v80, v199, v80, vcc
	v_cmp_le_i32_e32 vcc, v216, v215
	v_add_u32_e32 v216, 0x79, v212
	s_nop 0
	v_cndmask_b32_e32 v97, v199, v97, vcc
	v_cmp_le_i32_e32 vcc, v216, v215
	v_add_u32_e32 v216, 0x5a, v212
	s_nop 0
	v_cndmask_b32_e32 v81, v199, v81, vcc
	v_cmp_le_i32_e32 vcc, v216, v215
	v_add_u32_e32 v216, 0x7a, v212
	s_nop 0
	v_cndmask_b32_e32 v98, v199, v98, vcc
	v_cmp_le_i32_e32 vcc, v216, v215
	v_add_u32_e32 v216, 0x5b, v212
	s_nop 0
	v_cndmask_b32_e32 v82, v199, v82, vcc
	v_cmp_le_i32_e32 vcc, v216, v215
	v_add_u32_e32 v216, 0x7b, v212
	s_nop 0
	v_cndmask_b32_e32 v99, v199, v99, vcc
	v_cmp_le_i32_e32 vcc, v216, v215
	v_max_f32_e32 v216, v85, v85
	v_max_f32_e32 v216, v217, v216
	v_max3_f32 v217, v86, v87, v69
	v_max3_f32 v216, v216, v68, v70
	v_max3_f32 v216, v216, v71, v88
	v_max3_f32 v217, v217, v90, v91
	v_max3_f32 v216, v216, v89, v72
	v_max3_f32 v217, v217, v74, v75
	v_max3_f32 v216, v216, v73, v92
	v_max3_f32 v217, v217, v94, v95
	v_max3_f32 v216, v216, v93, v76
	v_max3_f32 v217, v217, v78, v79
	v_cndmask_b32_e32 v83, v199, v83, vcc
	v_max3_f32 v216, v216, v77, v96
	v_max3_f32 v217, v217, v98, v99
	v_max3_f32 v216, v216, v97, v80
	v_max3_f32 v217, v217, v82, v83
	v_max3_f32 v216, v216, v81, v217
	v_mov_b32_e32 v217, v216
	s_nop 1
	v_permlane32_swap_b32_e32 v216, v217
	s_nop 0
	s_nop 0
	v_max_f32_e32 v216, v216, v217
	v_sub_f32_e32 v216, v216, v210
	v_cmp_lt_f32_e32 vcc, s66, v216
	s_cmp_lg_u64 vcc, 0
	s_cselect_b64 s[28:29], -1, 0
	s_cbranch_vccz .LBB0_2020
	v_max_f32_e32 v216, v216, v216
	v_max_f32_e32 v217, 0, v216
	v_exp_f32_e64 v216, -v217
	s_and_saveexec_b64 s[4:5], s[0:1]
	ds_write_b32 v207, v216 offset:49152
	s_or_b64 exec, exec, s[4:5]
	v_add_f32_e32 v210, v210, v217
	v_mul_f32_e32 v214, v214, v216

.LBB0_2045:
	v_add_u32_e32 v168, s59, v209
	ds_read_b64_tr_b16 v[164:165], v168 offset:24576
	ds_read_b64_tr_b16 v[166:167], v168 offset:25088
	s_waitcnt lgkmcnt(9)
	v_mfma_f32_32x32x16_bf16 v[52:67], v[160:163], v[128:131], v[52:67]
	v_add_f32_e32 v100, v84, v85
	v_add_f32_e32 v100, v86, v100
	v_add_f32_e32 v100, v87, v100
	v_add_f32_e32 v100, v88, v100
	v_add_f32_e32 v100, v89, v100
	v_cvt_pk_bf16_f32 v120, v84, v85
	v_cvt_pk_bf16_f32 v121, v86, v87
	ds_read_b64_tr_b16 v[160:161], v168 offset:28672
	ds_read_b64_tr_b16 v[162:163], v168 offset:29184
	s_waitcnt lgkmcnt(10)
	v_mfma_f32_32x32x16_bf16 v[36:51], v[156:159], v[128:131], v[36:51]
	v_add_f32_e32 v84, v90, v100
	v_add_f32_e32 v84, v91, v84
	v_add_f32_e32 v84, v92, v84
	v_add_f32_e32 v84, v93, v84
	v_cvt_pk_bf16_f32 v122, v88, v89
	v_cvt_pk_bf16_f32 v123, v90, v91
	ds_read_b64_tr_b16 v[128:129], v168 offset:25600
	ds_read_b64_tr_b16 v[130:131], v168 offset:26112
	s_waitcnt lgkmcnt(11)
	v_mfma_f32_32x32x16_bf16 v[52:67], v[152:155], v[124:127], v[52:67]
	v_add_f32_e32 v84, v94, v84
	v_add_f32_e32 v84, v95, v84
	v_add_f32_e32 v84, v96, v84
	v_add_f32_e32 v84, v97, v84
	v_cvt_pk_bf16_f32 v112, v92, v93
	v_cvt_pk_bf16_f32 v113, v94, v95
	ds_read_b64_tr_b16 v[92:93], v168 offset:29696
	ds_read_b64_tr_b16 v[94:95], v168 offset:30208
	s_waitcnt lgkmcnt(12)
	v_mfma_f32_32x32x16_bf16 v[36:51], v[148:151], v[124:127], v[36:51]
	v_add_f32_e32 v84, v98, v84
	v_add_f32_e32 v84, v99, v84
	v_add_f32_e32 v84, v68, v84
	v_add_f32_e32 v84, v69, v84
	v_cvt_pk_bf16_f32 v114, v96, v97
	v_cvt_pk_bf16_f32 v115, v98, v99
	ds_read_b64_tr_b16 v[88:89], v168 offset:26624
	ds_read_b64_tr_b16 v[90:91], v168 offset:27136
	s_waitcnt lgkmcnt(13)
	v_mfma_f32_32x32x16_bf16 v[52:67], v[144:147], v[116:119], v[52:67]
	v_add_f32_e32 v84, v70, v84
	v_add_f32_e32 v84, v71, v84
	v_add_f32_e32 v84, v72, v84
	v_add_f32_e32 v96, v73, v84
	v_cvt_pk_bf16_f32 v104, v68, v69
	v_cvt_pk_bf16_f32 v105, v70, v71
	ds_read_b64_tr_b16 v[84:85], v168 offset:30720
	ds_read_b64_tr_b16 v[86:87], v168 offset:31232
	s_waitcnt lgkmcnt(14)
	v_mfma_f32_32x32x16_bf16 v[36:51], v[140:143], v[116:119], v[36:51]
	v_add_f32_e32 v68, v74, v96
	v_add_f32_e32 v68, v75, v68
	v_add_f32_e32 v68, v76, v68
	v_add_f32_e32 v68, v77, v68
	v_cvt_pk_bf16_f32 v106, v72, v73
	v_cvt_pk_bf16_f32 v107, v74, v75
	ds_read_b64_tr_b16 v[72:73], v168 offset:27648
	ds_read_b64_tr_b16 v[74:75], v168 offset:28160
	s_waitcnt lgkmcnt(14)
	v_mfma_f32_32x32x16_bf16 v[52:67], v[136:139], v[108:111], v[52:67]
	v_add_f32_e32 v68, v78, v68
	v_add_f32_e32 v68, v79, v68
	v_add_f32_e32 v68, v80, v68
	v_add_f32_e32 v96, v81, v68
	v_cvt_pk_bf16_f32 v100, v76, v77
	v_cvt_pk_bf16_f32 v101, v78, v79
	ds_read_b64_tr_b16 v[68:69], v168 offset:31744
	ds_read_b64_tr_b16 v[70:71], v168 offset:32256
	v_mfma_f32_32x32x16_bf16 v[36:51], v[132:135], v[108:111], v[36:51]
	v_add_f32_e32 v76, v82, v96
	v_add_f32_e32 v76, v83, v76
	s_nop 0
	v_cvt_pk_bf16_f32 v102, v80, v81
	v_cvt_pk_bf16_f32 v103, v82, v83
	v_or_b32_e32 v78, 0xe0, v208
	v_or_b32_e32 v77, 0xc0, v208
	v_cmp_le_i32_e32 vcc, v78, v215
	v_add_f32_e32 v76, v214, v76
	s_nop 3
	v_cndmask_b32_e32 v36, v199, v36, vcc
	v_cmp_lt_i32_e32 vcc, v77, v215
	s_nop 1
	v_cndmask_b32_e32 v53, v199, v53, vcc
	v_cmp_le_i32_e32 vcc, v77, v215
	v_or_b32_e32 v77, 0xe1, v208
	s_nop 0
	v_cndmask_b32_e32 v52, v199, v52, vcc
	v_cmp_le_i32_e32 vcc, v77, v215
	v_or_b32_e32 v77, 0xc2, v208
	v_max_f32_e32 v78, v52, v52
	v_cndmask_b32_e32 v37, v199, v37, vcc
	v_cmp_le_i32_e32 vcc, v77, v215
	v_or_b32_e32 v77, 0xe2, v208
	s_nop 0
	v_cndmask_b32_e32 v54, v199, v54, vcc
	v_cmp_le_i32_e32 vcc, v77, v215
	v_or_b32_e32 v77, 0xc3, v208
	s_nop 0
	v_cndmask_b32_e32 v38, v199, v38, vcc
	v_cmp_le_i32_e32 vcc, v77, v215
	v_or_b32_e32 v77, 0xe3, v208
	s_nop 0
	v_cndmask_b32_e32 v55, v199, v55, vcc
	v_cmp_le_i32_e32 vcc, v77, v215
	v_or_b32_e32 v77, 0xc8, v208
	s_nop 0
	v_cndmask_b32_e32 v39, v199, v39, vcc
	v_cmp_le_i32_e32 vcc, v77, v215
	v_or_b32_e32 v77, 0xe8, v208
	s_nop 0
	v_cndmask_b32_e32 v56, v199, v56, vcc
	v_cmp_le_i32_e32 vcc, v77, v215
	v_or_b32_e32 v77, 0xc9, v208
	s_nop 0
	v_cndmask_b32_e32 v40, v199, v40, vcc
	v_cmp_le_i32_e32 vcc, v77, v215
	v_or_b32_e32 v77, 0xe9, v208
	s_nop 0
	v_cndmask_b32_e32 v57, v199, v57, vcc
	v_cmp_le_i32_e32 vcc, v77, v215
	v_or_b32_e32 v77, 0xca, v208
	s_nop 0
	v_cndmask_b32_e32 v41, v199, v41, vcc
	v_cmp_le_i32_e32 vcc, v77, v215
	v_or_b32_e32 v77, 0xea, v208
	s_nop 0
	v_cndmask_b32_e32 v58, v199, v58, vcc
	v_cmp_le_i32_e32 vcc, v77, v215
	v_or_b32_e32 v77, 0xcb, v208
	s_nop 0
	v_cndmask_b32_e32 v42, v199, v42, vcc
	v_cmp_le_i32_e32 vcc, v77, v215
	v_or_b32_e32 v77, 0xeb, v208
	s_nop 0
	v_cndmask_b32_e32 v59, v199, v59, vcc
	v_cmp_le_i32_e32 vcc, v77, v215
	v_or_b32_e32 v77, 0xd0, v208
	s_nop 0
	v_cndmask_b32_e32 v43, v199, v43, vcc
	v_cmp_le_i32_e32 vcc, v77, v215
	v_or_b32_e32 v77, 0xf0, v208
	s_nop 0
	v_cndmask_b32_e32 v60, v199, v60, vcc
	v_cmp_le_i32_e32 vcc, v77, v215
	v_or_b32_e32 v77, 0xd1, v208
	s_nop 0
	v_cndmask_b32_e32 v44, v199, v44, vcc
	v_cmp_le_i32_e32 vcc, v77, v215
	v_or_b32_e32 v77, 0xf1, v208
	s_nop 0
	v_cndmask_b32_e32 v61, v199, v61, vcc
	v_cmp_le_i32_e32 vcc, v77, v215
	v_or_b32_e32 v77, 0xd2, v208
	s_nop 0
	v_cndmask_b32_e32 v45, v199, v45, vcc
	v_cmp_le_i32_e32 vcc, v77, v215
	v_or_b32_e32 v77, 0xf2, v208
	s_nop 0
	v_cndmask_b32_e32 v62, v199, v62, vcc
	v_cmp_le_i32_e32 vcc, v77, v215
	v_or_b32_e32 v77, 0xd3, v208
	s_nop 0
	v_cndmask_b32_e32 v46, v199, v46, vcc
	v_cmp_le_i32_e32 vcc, v77, v215
	v_or_b32_e32 v77, 0xf3, v208
	s_nop 0
	v_cndmask_b32_e32 v63, v199, v63, vcc
	v_cmp_le_i32_e32 vcc, v77, v215
	v_or_b32_e32 v77, 0xd8, v208
	s_nop 0
	v_cndmask_b32_e32 v47, v199, v47, vcc
	v_cmp_le_i32_e32 vcc, v77, v215
	v_or_b32_e32 v77, 0xf8, v208
	s_nop 0
	v_cndmask_b32_e32 v64, v199, v64, vcc
	v_cmp_le_i32_e32 vcc, v77, v215
	v_or_b32_e32 v77, 0xd9, v208
	s_nop 0
	v_cndmask_b32_e32 v48, v199, v48, vcc
	v_cmp_le_i32_e32 vcc, v77, v215
	v_or_b32_e32 v77, 0xf9, v208
	s_nop 0
	v_cndmask_b32_e32 v65, v199, v65, vcc
	v_cmp_le_i32_e32 vcc, v77, v215
	v_or_b32_e32 v77, 0xda, v208
	s_nop 0
	v_cndmask_b32_e32 v49, v199, v49, vcc
	v_cmp_le_i32_e32 vcc, v77, v215
	v_or_b32_e32 v77, 0xfa, v208
	s_nop 0
	v_cndmask_b32_e32 v66, v199, v66, vcc
	v_cmp_le_i32_e32 vcc, v77, v215
	v_or_b32_e32 v77, 0xdb, v208
	s_nop 0
	v_cndmask_b32_e32 v50, v199, v50, vcc
	v_cmp_le_i32_e32 vcc, v77, v215
	v_or_b32_e32 v77, 0xfb, v208
	s_nop 0
	v_cndmask_b32_e32 v67, v199, v67, vcc
	v_cmp_le_i32_e32 vcc, v77, v215
	v_max_f32_e32 v77, v53, v53
	v_max_f32_e32 v77, v78, v77
	v_max3_f32 v78, v54, v55, v37
	v_max3_f32 v77, v77, v36, v38
	v_max3_f32 v77, v77, v39, v56
	v_max3_f32 v78, v78, v58, v59
	v_max3_f32 v77, v77, v57, v40
	v_max3_f32 v78, v78, v42, v43
	v_max3_f32 v77, v77, v41, v60
	v_max3_f32 v78, v78, v62, v63
	v_max3_f32 v77, v77, v61, v44
	v_max3_f32 v78, v78, v46, v47
	v_cndmask_b32_e32 v51, v199, v51, vcc
	v_max3_f32 v77, v77, v45, v64
	v_max3_f32 v78, v78, v66, v67
	v_max3_f32 v77, v77, v65, v48
	v_max3_f32 v78, v78, v50, v51
	v_max3_f32 v77, v77, v49, v78
	v_mov_b32_e32 v78, v77
	s_nop 1
	v_permlane32_swap_b32_e32 v77, v78
	s_nop 0
	s_nop 0
	v_max_f32_e32 v77, v77, v78
	v_sub_f32_e32 v77, v77, v210
	v_cmp_lt_f32_e32 vcc, s66, v77
	s_cmp_lg_u64 vcc, 0
	s_cselect_b64 s[6:7], -1, 0
	s_cbranch_vccz .LBB0_2049
	v_max_f32_e32 v77, v77, v77
	v_max_f32_e32 v78, 0, v77
	v_exp_f32_e64 v77, -v78
	s_and_saveexec_b64 s[4:5], s[0:1]
	ds_write_b32 v207, v77 offset:49152
	s_or_b64 exec, exec, s[4:5]
	v_add_f32_e32 v210, v210, v78
	v_mul_f32_e32 v76, v76, v77
